# K-loops: MFMAs inside each same-k group in snake order (consecutive MFMAs change one operand)
# baseline (speedup 1.0000x reference)
; #define PG8_STAGE(bufoff, gbase, voff) do { _Pragma("unroll") for (int _i = 0; _i < 2; ++_i) \
;         __builtin_amdgcn_global_load_lds((const __attribute__((address_space(1))) unsigned*)((const char*)(gbase) + (voff)[_i]), (LAS unsigned*)(lds + (bufoff) + ldsw + _i * 8192), 16, 0, 0); } while (0)
; #define PG8_LDA(dst, b, h) do { _Pragma("unroll") for (int m = 0; m < 4; ++m) _Pragma("unroll") for (int k = 0; k < 2; ++k) dst[m][k] = *(const LAS bf16x8*)(lds + PG8_SA(b, h) + aoff + m * 2048 + k * 1024); } while (0)
; #define PG8_LDB(dst, b, h) do { _Pragma("unroll") for (int n = 0; n < 2; ++n) _Pragma("unroll") for (int k = 0; k < 2; ++k) dst[n][k] = *(const LAS bf16x8*)(lds + PG8_SB(b, h) + boff + n * 2048 + k * 1024); } while (0)
; #define PG8_MMA(ai, bj, At, Bt) do { __builtin_amdgcn_s_setprio(1); _Pragma("unroll") for (int m = 0; m < 4; ++m) _Pragma("unroll") for (int n = 0; n < 2; ++n) _Pragma("unroll") for (int k = 0; k < 2; ++k) \
;         acc[ai][bj][m][n] = __builtin_amdgcn_mfma_f32_16x16x32_bf16(Bt[n][k], At[m][k], acc[ai][bj][m][n], 0, 0, 0); __builtin_amdgcn_s_setprio(0); } while (0)
; #define PG8_WAIT_V(n) asm volatile("s_waitcnt vmcnt(" #n ")" ::: "memory")
; #define PG8_WAIT_L(n) asm volatile("s_waitcnt lgkmcnt(" #n ")" ::: "memory")
; #define PG8_BAR __builtin_amdgcn_s_barrier()
; template <class Epi, class SchedT, bool ALIGN_EPI, bool SP2>
; __device__ __forceinline__ void gemm_phase(LAS unsigned char* lds, const int ldk, const int nt, const SchedT& S, const Epi& E) {
;     ...
;             const bool last = (t == nt - 2);
;             const char* a1 = cA + (size_t)(t + 1) * kstep;
;             const char* a2 = last ? nA : cA + (size_t)(t + 2) * kstep; const char* b2 = last ? nB : cB + (size_t)(t + 2) * kstep;
;             const char* a3 = a2 + kstep; const char* b3 = b2 + kstep;
;             if constexpr (SP2) {
;             PG8_LDB(B0, 0, 0); PG8_LDB(B1, 0, 1); PG8_SCHED; PG8_LDA(At, 0, 0); PG8_STAGE(PG8_SA(1, 1), a1 + hstep, voffA);
;             PG8_WAIT_V(8); PG8_WAIT_L(0); PG8_BAR; PG8_MMA(0, 0, At, B0); PG8_MMA(0, 1, At, B1); PG8_BAR; PG8_SCHED;
;             PG8_LDA(At, 0, 1); PG8_STAGE(PG8_SB(0, 0), b2, voffB); PG8_STAGE(PG8_SB(0, 1), b2 + hstepB, voffB); PG8_STAGE(PG8_SA(0, 0), a2, voffA);
;             PG8_WAIT_V(8); PG8_WAIT_L(0); PG8_BAR; PG8_MMA(1, 0, At, B0); PG8_MMA(1, 1, At, B1); PG8_BAR; PG8_SCHED;
.LBB0_123:
	s_add_u32 s12, s0, 0xfff80080
	s_addc_u32 s13, s1, -1
	s_add_i32 s34, 0, 0x10000
	s_cmp_eq_u32 s21, 28
	s_cselect_b32 s17, s61, s13
	s_cselect_b32 s16, s60, s12
	v_add_u32_e32 v0, s34, v212
	s_cselect_b32 s13, s31, s19
	s_cselect_b32 s12, s30, s18
	s_add_i32 s38, 0, 0x14000
	s_waitcnt lgkmcnt(0)
	ds_read_b128 v[132:135], v0
	ds_read_b128 v[136:139], v0 offset:1024
	ds_read_b128 v[140:143], v0 offset:2048
	ds_read_b128 v[144:147], v0 offset:3072
	v_add_u32_e32 v0, s38, v212
	ds_read_b128 v[148:151], v0
	ds_read_b128 v[152:155], v0 offset:1024
	ds_read_b128 v[184:187], v0 offset:2048
	ds_read_b128 v[188:191], v0 offset:3072
	v_lshl_add_u64 v[2:3], s[0:1], 0, v[180:181]
	s_add_i32 m0, s88, 0xc000
	ds_read_b128 v[192:195], v216
	ds_read_b128 v[196:199], v216 offset:1024
	ds_read_b128 v[200:203], v216 offset:2048
	ds_read_b128 v[204:207], v216 offset:3072
	ds_read_b128 v[218:221], v216 offset:4096
	ds_read_b128 v[222:225], v216 offset:5120
	ds_read_b128 v[226:229], v216 offset:6144
	ds_read_b128 v[230:233], v216 offset:7168
	global_load_lds_dwordx4 v[2:3], off
	v_lshl_add_u64 v[2:3], s[0:1], 0, v[182:183]
	s_add_i32 m0, s88, 0xe000
	s_nop 0
	global_load_lds_dwordx4 v[2:3], off
	s_waitcnt vmcnt(8)
	s_waitcnt lgkmcnt(0)
	s_barrier
	s_setprio 1
	s_waitcnt lgkmcnt(0)
	v_mfma_f32_16x16x32_bf16 v[128:131], v[132:135], v[192:195], v[128:131]
	v_mfma_f32_16x16x32_bf16 v[124:127], v[140:143], v[192:195], v[124:127]
	v_mfma_f32_16x16x32_bf16 v[108:111], v[140:143], v[200:203], v[108:111]
	v_mfma_f32_16x16x32_bf16 v[112:115], v[132:135], v[200:203], v[112:115]
	v_mfma_f32_16x16x32_bf16 v[96:99], v[132:135], v[218:221], v[96:99]
	v_mfma_f32_16x16x32_bf16 v[92:95], v[140:143], v[218:221], v[92:95]
	v_mfma_f32_16x16x32_bf16 v[76:79], v[140:143], v[226:229], v[76:79]
	v_mfma_f32_16x16x32_bf16 v[80:83], v[132:135], v[226:229], v[80:83]
	v_mfma_f32_16x16x32_bf16 v[128:131], v[136:139], v[196:199], v[128:131]
	v_mfma_f32_16x16x32_bf16 v[124:127], v[144:147], v[196:199], v[124:127]
	v_mfma_f32_16x16x32_bf16 v[108:111], v[144:147], v[204:207], v[108:111]
	v_mfma_f32_16x16x32_bf16 v[112:115], v[136:139], v[204:207], v[112:115]
	v_mfma_f32_16x16x32_bf16 v[96:99], v[136:139], v[222:225], v[96:99]
	v_mfma_f32_16x16x32_bf16 v[92:95], v[144:147], v[222:225], v[92:95]
	v_mfma_f32_16x16x32_bf16 v[76:79], v[144:147], v[230:233], v[76:79]
	v_mfma_f32_16x16x32_bf16 v[80:83], v[136:139], v[230:233], v[80:83]
	s_setprio 0
	s_setprio 1
	v_mfma_f32_16x16x32_bf16 v[120:123], v[148:151], v[192:195], v[120:123]
	v_mfma_f32_16x16x32_bf16 v[116:119], v[184:187], v[192:195], v[116:119]
	v_mfma_f32_16x16x32_bf16 v[100:103], v[184:187], v[200:203], v[100:103]
	v_mfma_f32_16x16x32_bf16 v[104:107], v[148:151], v[200:203], v[104:107]
	v_mfma_f32_16x16x32_bf16 v[88:91], v[148:151], v[218:221], v[88:91]
	v_mfma_f32_16x16x32_bf16 v[84:87], v[184:187], v[218:221], v[84:87]
	v_mfma_f32_16x16x32_bf16 v[68:71], v[184:187], v[226:229], v[68:71]
	v_mfma_f32_16x16x32_bf16 v[72:75], v[148:151], v[226:229], v[72:75]
	v_mfma_f32_16x16x32_bf16 v[120:123], v[152:155], v[196:199], v[120:123]
	v_mfma_f32_16x16x32_bf16 v[116:119], v[188:191], v[196:199], v[116:119]
	v_mfma_f32_16x16x32_bf16 v[100:103], v[188:191], v[204:207], v[100:103]
	v_mfma_f32_16x16x32_bf16 v[104:107], v[152:155], v[204:207], v[104:107]
	v_mfma_f32_16x16x32_bf16 v[88:91], v[152:155], v[222:225], v[88:91]
	v_mfma_f32_16x16x32_bf16 v[84:87], v[188:191], v[222:225], v[84:87]
	v_mfma_f32_16x16x32_bf16 v[68:71], v[188:191], v[230:233], v[68:71]
	v_mfma_f32_16x16x32_bf16 v[72:75], v[152:155], v[230:233], v[72:75]
	s_setprio 0
	s_barrier
	s_add_i32 s34, s34, s87
	v_lshl_add_u64 v[208:209], s[12:13], 0, v[158:159]
	s_mov_b32 m0, s34
	ds_read_b128 v[192:195], v216 offset:16384
	ds_read_b128 v[196:199], v216 offset:17408
	ds_read_b128 v[200:203], v216 offset:18432
	ds_read_b128 v[204:207], v216 offset:19456
	ds_read_b128 v[218:221], v216 offset:20480
	ds_read_b128 v[222:225], v216 offset:21504
	ds_read_b128 v[226:229], v216 offset:22528
	ds_read_b128 v[230:233], v216 offset:23552
	global_load_lds_dwordx4 v[208:209], off
	s_add_i32 m0, s34, 0x2000
	s_add_u32 s34, s12, 0x20000
	v_lshl_add_u64 v[234:235], s[12:13], 0, v[174:175]
	s_addc_u32 s35, s13, 0
	s_add_i32 s38, s38, s87
	global_load_lds_dwordx4 v[234:235], off
	v_lshl_add_u64 v[2:3], s[34:35], 0, v[158:159]
	s_mov_b32 m0, s38
	v_lshl_add_u64 v[236:237], s[16:17], 0, v[156:157]
	global_load_lds_dwordx4 v[2:3], off
	v_lshl_add_u64 v[2:3], s[34:35], 0, v[174:175]
	s_add_i32 m0, s38, 0x2000
	v_lshl_add_u64 v[238:239], s[16:17], 0, v[160:161]
	global_load_lds_dwordx4 v[2:3], off
	s_mov_b32 m0, s88
	s_nop 0
	global_load_lds_dwordx4 v[236:237], off
	s_mov_b32 m0, s89
	s_nop 0
	global_load_lds_dwordx4 v[238:239], off
	s_waitcnt vmcnt(8)
	s_waitcnt lgkmcnt(0)
	s_barrier
; #define PG8_STAGE(bufoff, gbase, voff) do { _Pragma("unroll") for (int _i = 0; _i < 2; ++_i) \
;         __builtin_amdgcn_global_load_lds((const __attribute__((address_space(1))) unsigned*)((const char*)(gbase) + (voff)[_i]), (LAS unsigned*)(lds + (bufoff) + ldsw + _i * 8192), 16, 0, 0); } while (0)
; #define PG8_LDA(dst, b, h) do { _Pragma("unroll") for (int m = 0; m < 4; ++m) _Pragma("unroll") for (int k = 0; k < 2; ++k) dst[m][k] = *(const LAS bf16x8*)(lds + PG8_SA(b, h) + aoff + m * 2048 + k * 1024); } while (0)
; #define PG8_LDB(dst, b, h) do { _Pragma("unroll") for (int n = 0; n < 2; ++n) _Pragma("unroll") for (int k = 0; k < 2; ++k) dst[n][k] = *(const LAS bf16x8*)(lds + PG8_SB(b, h) + boff + n * 2048 + k * 1024); } while (0)
; #define PG8_MMA(ai, bj, At, Bt) do { __builtin_amdgcn_s_setprio(1); _Pragma("unroll") for (int m = 0; m < 4; ++m) _Pragma("unroll") for (int n = 0; n < 2; ++n) _Pragma("unroll") for (int k = 0; k < 2; ++k) \
;         acc[ai][bj][m][n] = __builtin_amdgcn_mfma_f32_16x16x32_bf16(Bt[n][k], At[m][k], acc[ai][bj][m][n], 0, 0, 0); __builtin_amdgcn_s_setprio(0); } while (0)
; #define PG8_WAIT_V(n) asm volatile("s_waitcnt vmcnt(" #n ")" ::: "memory")
; #define PG8_WAIT_L(n) asm volatile("s_waitcnt lgkmcnt(" #n ")" ::: "memory")
; #define PG8_BAR __builtin_amdgcn_s_barrier()
; #define PG8_SCHED __builtin_amdgcn_sched_barrier(0)
; template <class Epi, class SchedT, bool ALIGN_EPI, bool SP2>
; __device__ __forceinline__ void gemm_phase(LAS unsigned char* lds, const int ldk, const int nt, const SchedT& S, const Epi& E) {
;     ...
;             PG8_WAIT_V(8); PG8_WAIT_L(0); PG8_BAR; PG8_MMA(0, 0, At, B0); PG8_MMA(0, 1, At, B1); PG8_BAR; PG8_SCHED;
;             PG8_LDA(At, 0, 1); PG8_STAGE(PG8_SB(0, 0), b2, voffB); PG8_STAGE(PG8_SB(0, 1), b2 + hstepB, voffB); PG8_STAGE(PG8_SA(0, 0), a2, voffA);
;             PG8_WAIT_V(8); PG8_WAIT_L(0); PG8_BAR; PG8_MMA(1, 0, At, B0); PG8_MMA(1, 1, At, B1); PG8_BAR; PG8_SCHED;
;             PG8_LDB(B0, 1, 0); PG8_LDB(B1, 1, 1); PG8_SCHED; PG8_LDA(At, 1, 0); PG8_STAGE(PG8_SA(0, 1), a2 + hstep, voffA);
;             PG8_WAIT_V(8); PG8_WAIT_L(0); PG8_BAR; PG8_MMA(0, 0, At, B0); PG8_MMA(0, 1, At, B1); PG8_BAR; PG8_SCHED;
	s_setprio 1
	s_waitcnt lgkmcnt(0)
	v_mfma_f32_16x16x32_bf16 v[64:67], v[132:135], v[192:195], v[64:67]
	v_mfma_f32_16x16x32_bf16 v[60:63], v[140:143], v[192:195], v[60:63]
	v_mfma_f32_16x16x32_bf16 v[44:47], v[140:143], v[200:203], v[44:47]
	v_mfma_f32_16x16x32_bf16 v[48:51], v[132:135], v[200:203], v[48:51]
	v_mfma_f32_16x16x32_bf16 v[32:35], v[132:135], v[218:221], v[32:35]
	v_mfma_f32_16x16x32_bf16 v[28:31], v[140:143], v[218:221], v[28:31]
	v_mfma_f32_16x16x32_bf16 v[12:15], v[140:143], v[226:229], v[12:15]
	v_mfma_f32_16x16x32_bf16 v[16:19], v[132:135], v[226:229], v[16:19]
	v_mfma_f32_16x16x32_bf16 v[64:67], v[136:139], v[196:199], v[64:67]
	v_mfma_f32_16x16x32_bf16 v[60:63], v[144:147], v[196:199], v[60:63]
	v_mfma_f32_16x16x32_bf16 v[44:47], v[144:147], v[204:207], v[44:47]
	v_mfma_f32_16x16x32_bf16 v[48:51], v[136:139], v[204:207], v[48:51]
	v_mfma_f32_16x16x32_bf16 v[32:35], v[136:139], v[222:225], v[32:35]
	v_mfma_f32_16x16x32_bf16 v[28:31], v[144:147], v[222:225], v[28:31]
	v_mfma_f32_16x16x32_bf16 v[12:15], v[144:147], v[230:233], v[12:15]
	v_mfma_f32_16x16x32_bf16 v[16:19], v[136:139], v[230:233], v[16:19]
	s_setprio 0
	s_setprio 1
	v_mfma_f32_16x16x32_bf16 v[56:59], v[148:151], v[192:195], v[56:59]
	v_mfma_f32_16x16x32_bf16 v[52:55], v[184:187], v[192:195], v[52:55]
	v_mfma_f32_16x16x32_bf16 v[36:39], v[184:187], v[200:203], v[36:39]
	v_mfma_f32_16x16x32_bf16 v[40:43], v[148:151], v[200:203], v[40:43]
	v_mfma_f32_16x16x32_bf16 v[24:27], v[148:151], v[218:221], v[24:27]
	v_mfma_f32_16x16x32_bf16 v[20:23], v[184:187], v[218:221], v[20:23]
	v_mfma_f32_16x16x32_bf16 v[2:5], v[184:187], v[226:229], v[4:7]
	v_mfma_f32_16x16x32_bf16 v[8:11], v[148:151], v[226:229], v[8:11]
	v_mfma_f32_16x16x32_bf16 v[56:59], v[152:155], v[196:199], v[56:59]
	v_mfma_f32_16x16x32_bf16 v[52:55], v[188:191], v[196:199], v[52:55]
	v_mfma_f32_16x16x32_bf16 v[36:39], v[188:191], v[204:207], v[36:39]
	v_mfma_f32_16x16x32_bf16 v[40:43], v[152:155], v[204:207], v[40:43]
	v_mfma_f32_16x16x32_bf16 v[24:27], v[152:155], v[222:225], v[24:27]
	v_mfma_f32_16x16x32_bf16 v[20:23], v[188:191], v[222:225], v[20:23]
	v_mfma_f32_16x16x32_bf16 v[2:5], v[188:191], v[230:233], v[2:5]
	v_mfma_f32_16x16x32_bf16 v[8:11], v[152:155], v[230:233], v[8:11]
	s_setprio 0
	s_barrier
	s_add_i32 s34, 0, 0x18000
	v_add_u32_e32 v0, s34, v212
	s_add_i32 s35, 0, 0x1c000
	ds_read_b128 v[132:135], v0
	ds_read_b128 v[136:139], v0 offset:1024
	ds_read_b128 v[140:143], v0 offset:2048
	ds_read_b128 v[144:147], v0 offset:3072
	v_add_u32_e32 v0, s35, v212
	ds_read_b128 v[148:151], v0
	ds_read_b128 v[152:155], v0 offset:1024
	ds_read_b128 v[184:187], v0 offset:2048
	ds_read_b128 v[188:191], v0 offset:3072
	s_add_u32 s16, s16, 0x80000
	s_addc_u32 s17, s17, 0
	s_mov_b32 m0, s90
	v_lshl_add_u64 v[6:7], s[16:17], 0, v[156:157]
	ds_read_b128 v[192:195], v216 offset:32768
	ds_read_b128 v[196:199], v216 offset:33792
	ds_read_b128 v[200:203], v216 offset:34816
	ds_read_b128 v[204:207], v216 offset:35840
	ds_read_b128 v[218:221], v216 offset:36864
	ds_read_b128 v[222:225], v216 offset:37888
	ds_read_b128 v[226:229], v216 offset:38912
	ds_read_b128 v[230:233], v216 offset:39936
	global_load_lds_dwordx4 v[6:7], off
	v_lshl_add_u64 v[6:7], s[16:17], 0, v[160:161]
	s_mov_b32 m0, s91
	s_nop 0
	global_load_lds_dwordx4 v[6:7], off
	s_waitcnt vmcnt(8)
	s_waitcnt lgkmcnt(0)
	s_barrier
	s_setprio 1
	s_waitcnt lgkmcnt(0)
	v_mfma_f32_16x16x32_bf16 v[128:131], v[132:135], v[192:195], v[128:131]
	v_mfma_f32_16x16x32_bf16 v[124:127], v[140:143], v[192:195], v[124:127]
	v_mfma_f32_16x16x32_bf16 v[108:111], v[140:143], v[200:203], v[108:111]
	v_mfma_f32_16x16x32_bf16 v[112:115], v[132:135], v[200:203], v[112:115]
	v_mfma_f32_16x16x32_bf16 v[96:99], v[132:135], v[218:221], v[96:99]
	v_mfma_f32_16x16x32_bf16 v[92:95], v[140:143], v[218:221], v[92:95]
	v_mfma_f32_16x16x32_bf16 v[76:79], v[140:143], v[226:229], v[76:79]
	v_mfma_f32_16x16x32_bf16 v[80:83], v[132:135], v[226:229], v[80:83]
	v_mfma_f32_16x16x32_bf16 v[128:131], v[136:139], v[196:199], v[128:131]
	v_mfma_f32_16x16x32_bf16 v[124:127], v[144:147], v[196:199], v[124:127]
	v_mfma_f32_16x16x32_bf16 v[108:111], v[144:147], v[204:207], v[108:111]
	v_mfma_f32_16x16x32_bf16 v[112:115], v[136:139], v[204:207], v[112:115]
	v_mfma_f32_16x16x32_bf16 v[96:99], v[136:139], v[222:225], v[96:99]
	v_mfma_f32_16x16x32_bf16 v[92:95], v[144:147], v[222:225], v[92:95]
	v_mfma_f32_16x16x32_bf16 v[76:79], v[144:147], v[230:233], v[76:79]
	v_mfma_f32_16x16x32_bf16 v[80:83], v[136:139], v[230:233], v[80:83]
	s_setprio 0
	s_setprio 1
	v_mfma_f32_16x16x32_bf16 v[120:123], v[148:151], v[192:195], v[120:123]
	v_mfma_f32_16x16x32_bf16 v[116:119], v[184:187], v[192:195], v[116:119]
	v_mfma_f32_16x16x32_bf16 v[100:103], v[184:187], v[200:203], v[100:103]
	v_mfma_f32_16x16x32_bf16 v[104:107], v[148:151], v[200:203], v[104:107]
	v_mfma_f32_16x16x32_bf16 v[88:91], v[148:151], v[218:221], v[88:91]
	v_mfma_f32_16x16x32_bf16 v[84:87], v[184:187], v[218:221], v[84:87]
	v_mfma_f32_16x16x32_bf16 v[68:71], v[184:187], v[226:229], v[68:71]
	v_mfma_f32_16x16x32_bf16 v[72:75], v[148:151], v[226:229], v[72:75]
	v_mfma_f32_16x16x32_bf16 v[120:123], v[152:155], v[196:199], v[120:123]
	v_mfma_f32_16x16x32_bf16 v[116:119], v[188:191], v[196:199], v[116:119]
	v_mfma_f32_16x16x32_bf16 v[100:103], v[188:191], v[204:207], v[100:103]
	v_mfma_f32_16x16x32_bf16 v[104:107], v[152:155], v[204:207], v[104:107]
	v_mfma_f32_16x16x32_bf16 v[88:91], v[152:155], v[222:225], v[88:91]
	v_mfma_f32_16x16x32_bf16 v[84:87], v[188:191], v[222:225], v[84:87]
	v_mfma_f32_16x16x32_bf16 v[68:71], v[188:191], v[230:233], v[68:71]
	v_mfma_f32_16x16x32_bf16 v[72:75], v[152:155], v[230:233], v[72:75]
	s_setprio 0
	s_barrier
; #define PG8_STAGE(bufoff, gbase, voff) do { _Pragma("unroll") for (int _i = 0; _i < 2; ++_i) \
;         __builtin_amdgcn_global_load_lds((const __attribute__((address_space(1))) unsigned*)((const char*)(gbase) + (voff)[_i]), (LAS unsigned*)(lds + (bufoff) + ldsw + _i * 8192), 16, 0, 0); } while (0)
; #define PG8_LDA(dst, b, h) do { _Pragma("unroll") for (int m = 0; m < 4; ++m) _Pragma("unroll") for (int k = 0; k < 2; ++k) dst[m][k] = *(const LAS bf16x8*)(lds + PG8_SA(b, h) + aoff + m * 2048 + k * 1024); } while (0)
; #define PG8_MMA(ai, bj, At, Bt) do { __builtin_amdgcn_s_setprio(1); _Pragma("unroll") for (int m = 0; m < 4; ++m) _Pragma("unroll") for (int n = 0; n < 2; ++n) _Pragma("unroll") for (int k = 0; k < 2; ++k) \
;         acc[ai][bj][m][n] = __builtin_amdgcn_mfma_f32_16x16x32_bf16(Bt[n][k], At[m][k], acc[ai][bj][m][n], 0, 0, 0); __builtin_amdgcn_s_setprio(0); } while (0)
; #define PG8_WAIT_V(n) asm volatile("s_waitcnt vmcnt(" #n ")" ::: "memory")
; #define PG8_WAIT_L(n) asm volatile("s_waitcnt lgkmcnt(" #n ")" ::: "memory")
; #define PG8_BAR __builtin_amdgcn_s_barrier()
; #define PG8_SCHED __builtin_amdgcn_sched_barrier(0)
; template <class Epi, class SchedT, bool ALIGN_EPI, bool SP2>
; __device__ __forceinline__ void gemm_phase(LAS unsigned char* lds, const int ldk, const int nt, const SchedT& S, const Epi& E) {
;     ...
;             PG8_LDA(At, 1, 1); PG8_STAGE(PG8_SB(1, 0), b3, voffB); PG8_STAGE(PG8_SB(1, 1), b3 + hstepB, voffB); PG8_STAGE(PG8_SA(1, 0), a3, voffA);
;             PG8_WAIT_V(8); PG8_WAIT_L(0); PG8_BAR; PG8_MMA(1, 0, At, B0); PG8_MMA(1, 1, At, B1); PG8_BAR; PG8_SCHED;
;     ...
;         if constexpr (ALIGN_EPI) { if (wr == 0) PG8_BAR; }
	s_add_i32 s16, s34, s87
	v_lshl_add_u64 v[6:7], v[208:209], 0, s[24:25]
	s_mov_b32 m0, s16
	ds_read_b128 v[192:195], v216 offset:49152
	ds_read_b128 v[196:199], v216 offset:50176
	ds_read_b128 v[200:203], v216 offset:51200
	ds_read_b128 v[204:207], v216 offset:52224
	ds_read_b128 v[218:221], v216 offset:53248
	ds_read_b128 v[222:225], v216 offset:54272
	ds_read_b128 v[226:229], v216 offset:55296
	ds_read_b128 v[230:233], v216 offset:56320
	global_load_lds_dwordx4 v[6:7], off
	s_add_i32 m0, s16, 0x2000
	s_add_u32 s12, s12, 0x20080
	v_lshl_add_u64 v[6:7], v[234:235], 0, s[24:25]
	s_addc_u32 s13, s13, 0
	s_add_i32 s16, s35, s87
	global_load_lds_dwordx4 v[6:7], off
	v_lshl_add_u64 v[6:7], s[12:13], 0, v[158:159]
	s_mov_b32 m0, s16
	s_nop 0
	global_load_lds_dwordx4 v[6:7], off
	v_lshl_add_u64 v[6:7], s[12:13], 0, v[174:175]
	s_add_i32 m0, s16, 0x2000
	s_nop 0
	global_load_lds_dwordx4 v[6:7], off
	v_lshl_add_u64 v[6:7], v[236:237], 0, s[24:25]
	s_mov_b32 m0, s92
	s_nop 0
	global_load_lds_dwordx4 v[6:7], off
	v_lshl_add_u64 v[6:7], v[238:239], 0, s[24:25]
	s_mov_b32 m0, s93
	s_nop 0
	global_load_lds_dwordx4 v[6:7], off
	s_waitcnt vmcnt(8)
	s_waitcnt lgkmcnt(0)
	s_barrier
	s_setprio 1
	s_waitcnt lgkmcnt(0)
	v_mfma_f32_16x16x32_bf16 v[64:67], v[132:135], v[192:195], v[64:67]
	v_mfma_f32_16x16x32_bf16 v[60:63], v[140:143], v[192:195], v[60:63]
	v_mfma_f32_16x16x32_bf16 v[44:47], v[140:143], v[200:203], v[44:47]
	v_mfma_f32_16x16x32_bf16 v[48:51], v[132:135], v[200:203], v[48:51]
	v_mfma_f32_16x16x32_bf16 v[32:35], v[132:135], v[218:221], v[32:35]
	v_mfma_f32_16x16x32_bf16 v[28:31], v[140:143], v[218:221], v[28:31]
	v_mfma_f32_16x16x32_bf16 v[12:15], v[140:143], v[226:229], v[12:15]
	v_mfma_f32_16x16x32_bf16 v[16:19], v[132:135], v[226:229], v[16:19]
	v_mfma_f32_16x16x32_bf16 v[64:67], v[136:139], v[196:199], v[64:67]
	v_mfma_f32_16x16x32_bf16 v[60:63], v[144:147], v[196:199], v[60:63]
	v_mfma_f32_16x16x32_bf16 v[44:47], v[144:147], v[204:207], v[44:47]
	v_mfma_f32_16x16x32_bf16 v[48:51], v[136:139], v[204:207], v[48:51]
	v_mfma_f32_16x16x32_bf16 v[32:35], v[136:139], v[222:225], v[32:35]
	v_mfma_f32_16x16x32_bf16 v[28:31], v[144:147], v[222:225], v[28:31]
	v_mfma_f32_16x16x32_bf16 v[12:15], v[144:147], v[230:233], v[12:15]
	v_mfma_f32_16x16x32_bf16 v[16:19], v[136:139], v[230:233], v[16:19]
	s_setprio 0
	s_setprio 1
	v_mfma_f32_16x16x32_bf16 v[56:59], v[148:151], v[192:195], v[56:59]
	v_mfma_f32_16x16x32_bf16 v[52:55], v[184:187], v[192:195], v[52:55]
	v_mfma_f32_16x16x32_bf16 v[36:39], v[184:187], v[200:203], v[36:39]
	v_mfma_f32_16x16x32_bf16 v[40:43], v[148:151], v[200:203], v[40:43]
	v_mfma_f32_16x16x32_bf16 v[24:27], v[148:151], v[218:221], v[24:27]
	v_mfma_f32_16x16x32_bf16 v[20:23], v[184:187], v[218:221], v[20:23]
	v_mfma_f32_16x16x32_bf16 v[2:5], v[184:187], v[226:229], v[2:5]
	v_mfma_f32_16x16x32_bf16 v[6:9], v[148:151], v[226:229], v[8:11]
	v_mfma_f32_16x16x32_bf16 v[56:59], v[152:155], v[196:199], v[56:59]
	v_mfma_f32_16x16x32_bf16 v[52:55], v[188:191], v[196:199], v[52:55]
	v_mfma_f32_16x16x32_bf16 v[36:39], v[188:191], v[204:207], v[36:39]
	v_mfma_f32_16x16x32_bf16 v[40:43], v[152:155], v[204:207], v[40:43]
	v_mfma_f32_16x16x32_bf16 v[24:27], v[152:155], v[222:225], v[24:27]
	v_mfma_f32_16x16x32_bf16 v[20:23], v[188:191], v[222:225], v[20:23]
	v_mfma_f32_16x16x32_bf16 v[8:11], v[152:155], v[230:233], v[6:9]
	v_mfma_f32_16x16x32_bf16 v[4:7], v[188:191], v[230:233], v[2:5]
	s_setprio 0
	s_barrier
	s_add_i32 s21, s21, 2
	s_add_u32 s0, s0, 0x100
	s_addc_u32 s1, s1, 0
	s_add_u32 s18, s18, 0x100
	s_addc_u32 s19, s19, 0
	s_cmp_gt_u32 s21, 29
	s_cbranch_scc0 .LBB0_123
	s_and_b64 vcc, exec, s[58:59]
	s_cbranch_vccz .LBB0_126
	s_barrier

; #define PG8_STAGE(bufoff, gbase, voff) do { _Pragma("unroll") for (int _i = 0; _i < 2; ++_i) \
;         __builtin_amdgcn_global_load_lds((const __attribute__((address_space(1))) unsigned*)((const char*)(gbase) + (voff)[_i]), (LAS unsigned*)(lds + (bufoff) + ldsw + _i * 8192), 16, 0, 0); } while (0)
; #define PG8_LDA(dst, b, h) do { _Pragma("unroll") for (int m = 0; m < 4; ++m) _Pragma("unroll") for (int k = 0; k < 2; ++k) dst[m][k] = *(const LAS bf16x8*)(lds + PG8_SA(b, h) + aoff + m * 2048 + k * 1024); } while (0)
; #define PG8_LDB(dst, b, h) do { _Pragma("unroll") for (int n = 0; n < 2; ++n) _Pragma("unroll") for (int k = 0; k < 2; ++k) dst[n][k] = *(const LAS bf16x8*)(lds + PG8_SB(b, h) + boff + n * 2048 + k * 1024); } while (0)
; #define PG8_MMA(ai, bj, At, Bt) do { __builtin_amdgcn_s_setprio(1); _Pragma("unroll") for (int m = 0; m < 4; ++m) _Pragma("unroll") for (int n = 0; n < 2; ++n) _Pragma("unroll") for (int k = 0; k < 2; ++k) \
;         acc[ai][bj][m][n] = __builtin_amdgcn_mfma_f32_16x16x32_bf16(Bt[n][k], At[m][k], acc[ai][bj][m][n], 0, 0, 0); __builtin_amdgcn_s_setprio(0); } while (0)
; #define PG8_WAIT_V(n) asm volatile("s_waitcnt vmcnt(" #n ")" ::: "memory")
; #define PG8_WAIT_L(n) asm volatile("s_waitcnt lgkmcnt(" #n ")" ::: "memory")
; #define PG8_BAR __builtin_amdgcn_s_barrier()
; #define PG8_SCHED __builtin_amdgcn_sched_barrier(0)
; template <class Epi, class SchedT, bool ALIGN_EPI, bool SP2>
; __device__ __forceinline__ void gemm_phase(LAS unsigned char* lds, const int ldk, const int nt, const SchedT& S, const Epi& E) {
;     ...
;             const bool last = (t == nt - 2);
;             const char* a1 = cA + (size_t)(t + 1) * kstep;
;             const char* a2 = last ? nA : cA + (size_t)(t + 2) * kstep; const char* b2 = last ? nB : cB + (size_t)(t + 2) * kstep;
;             const char* a3 = a2 + kstep; const char* b3 = b2 + kstep;
;             if constexpr (SP2) {
;             PG8_LDB(B0, 0, 0); PG8_LDB(B1, 0, 1); PG8_SCHED; PG8_LDA(At, 0, 0); PG8_STAGE(PG8_SA(1, 1), a1 + hstep, voffA);
;             PG8_WAIT_V(8); PG8_WAIT_L(0); PG8_BAR; PG8_MMA(0, 0, At, B0); PG8_MMA(0, 1, At, B1); PG8_BAR; PG8_SCHED;
;             PG8_LDA(At, 0, 1); PG8_STAGE(PG8_SB(0, 0), b2, voffB); PG8_STAGE(PG8_SB(0, 1), b2 + hstepB, voffB); PG8_STAGE(PG8_SA(0, 0), a2, voffA);
.LBB0_534:
	s_add_u32 s36, s34, 0xfff80080
	s_addc_u32 s37, s35, -1
	s_add_i32 s49, 0, 0x10000
	s_cmp_eq_u32 s47, 12
	s_cselect_b32 s41, s1, s37
	s_cselect_b32 s40, s0, s36
	v_add_u32_e32 v0, s49, v159
	s_cselect_b32 s37, s53, s20
	s_cselect_b32 s36, s52, s17
	s_add_i32 s51, 0, 0x14000
	ds_read_b128 v[144:147], v0
	ds_read_b128 v[148:151], v0 offset:1024
	ds_read_b128 v[152:155], v0 offset:2048
	ds_read_b128 v[174:177], v0 offset:3072
	v_add_u32_e32 v0, s51, v159
	ds_read_b128 v[178:181], v0
	ds_read_b128 v[182:185], v0 offset:1024
	ds_read_b128 v[186:189], v0 offset:2048
	ds_read_b128 v[190:193], v0 offset:3072
	v_lshl_add_u64 v[2:3], s[34:35], 0, v[140:141]
	s_add_i32 m0, s57, 0xc000
	ds_read_b128 v[194:197], v161
	ds_read_b128 v[198:201], v161 offset:1024
	ds_read_b128 v[202:205], v161 offset:2048
	ds_read_b128 v[206:209], v161 offset:3072
	ds_read_b128 v[210:213], v161 offset:4096
	ds_read_b128 v[214:217], v161 offset:5120
	ds_read_b128 v[218:221], v161 offset:6144
	ds_read_b128 v[222:225], v161 offset:7168
	global_load_lds_dwordx4 v[2:3], off
	v_lshl_add_u64 v[2:3], s[34:35], 0, v[142:143]
	s_add_i32 m0, s57, 0xe000
	s_nop 0
	global_load_lds_dwordx4 v[2:3], off
	s_waitcnt vmcnt(8)
	s_waitcnt lgkmcnt(0)
	s_barrier
	s_setprio 1
	s_waitcnt lgkmcnt(0)
	v_mfma_f32_16x16x32_bf16 v[128:131], v[144:147], v[194:197], v[128:131]
	v_mfma_f32_16x16x32_bf16 v[124:127], v[152:155], v[194:197], v[124:127]
	v_mfma_f32_16x16x32_bf16 v[116:119], v[152:155], v[202:205], v[116:119]
	v_mfma_f32_16x16x32_bf16 v[120:123], v[144:147], v[202:205], v[120:123]
	v_mfma_f32_16x16x32_bf16 v[112:115], v[144:147], v[210:213], v[112:115]
	v_mfma_f32_16x16x32_bf16 v[108:111], v[152:155], v[210:213], v[108:111]
	v_mfma_f32_16x16x32_bf16 v[100:103], v[152:155], v[218:221], v[100:103]
	v_mfma_f32_16x16x32_bf16 v[104:107], v[144:147], v[218:221], v[104:107]
	v_mfma_f32_16x16x32_bf16 v[128:131], v[148:151], v[198:201], v[128:131]
	v_mfma_f32_16x16x32_bf16 v[124:127], v[174:177], v[198:201], v[124:127]
	v_mfma_f32_16x16x32_bf16 v[116:119], v[174:177], v[206:209], v[116:119]
	v_mfma_f32_16x16x32_bf16 v[120:123], v[148:151], v[206:209], v[120:123]
	v_mfma_f32_16x16x32_bf16 v[112:115], v[148:151], v[214:217], v[112:115]
	v_mfma_f32_16x16x32_bf16 v[108:111], v[174:177], v[214:217], v[108:111]
	v_mfma_f32_16x16x32_bf16 v[100:103], v[174:177], v[222:225], v[100:103]
	v_mfma_f32_16x16x32_bf16 v[104:107], v[148:151], v[222:225], v[104:107]
	s_setprio 0
	s_setprio 1
	v_mfma_f32_16x16x32_bf16 v[96:99], v[178:181], v[194:197], v[96:99]
	v_mfma_f32_16x16x32_bf16 v[92:95], v[186:189], v[194:197], v[92:95]
	v_mfma_f32_16x16x32_bf16 v[84:87], v[186:189], v[202:205], v[84:87]
	v_mfma_f32_16x16x32_bf16 v[88:91], v[178:181], v[202:205], v[88:91]
	v_mfma_f32_16x16x32_bf16 v[80:83], v[178:181], v[210:213], v[80:83]
	v_mfma_f32_16x16x32_bf16 v[76:79], v[186:189], v[210:213], v[76:79]
	v_mfma_f32_16x16x32_bf16 v[68:71], v[186:189], v[218:221], v[68:71]
	v_mfma_f32_16x16x32_bf16 v[72:75], v[178:181], v[218:221], v[72:75]
	v_mfma_f32_16x16x32_bf16 v[96:99], v[182:185], v[198:201], v[96:99]
	v_mfma_f32_16x16x32_bf16 v[92:95], v[190:193], v[198:201], v[92:95]
	v_mfma_f32_16x16x32_bf16 v[84:87], v[190:193], v[206:209], v[84:87]
	v_mfma_f32_16x16x32_bf16 v[88:91], v[182:185], v[206:209], v[88:91]
	v_mfma_f32_16x16x32_bf16 v[80:83], v[182:185], v[214:217], v[80:83]
	v_mfma_f32_16x16x32_bf16 v[76:79], v[190:193], v[214:217], v[76:79]
	v_mfma_f32_16x16x32_bf16 v[68:71], v[190:193], v[222:225], v[68:71]
	v_mfma_f32_16x16x32_bf16 v[72:75], v[182:185], v[222:225], v[72:75]
	s_setprio 0
	s_barrier
	s_add_i32 s49, s49, s56
	v_lshl_add_u64 v[156:157], s[36:37], 0, v[134:135]
	s_mov_b32 m0, s49
	ds_read_b128 v[194:197], v161 offset:16384
	ds_read_b128 v[198:201], v161 offset:17408
	ds_read_b128 v[202:205], v161 offset:18432
	ds_read_b128 v[206:209], v161 offset:19456
	ds_read_b128 v[210:213], v161 offset:20480
	ds_read_b128 v[214:217], v161 offset:21504
	ds_read_b128 v[218:221], v161 offset:22528
	ds_read_b128 v[222:225], v161 offset:23552
	global_load_lds_dwordx4 v[156:157], off
	s_add_i32 m0, s49, 0x2000
	s_add_u32 s82, s36, 0x20000
	v_lshl_add_u64 v[226:227], s[36:37], 0, v[138:139]
	s_addc_u32 s83, s37, 0
	s_add_i32 s49, s51, s56
	global_load_lds_dwordx4 v[226:227], off
	v_lshl_add_u64 v[2:3], s[82:83], 0, v[134:135]
	s_mov_b32 m0, s49
	v_lshl_add_u64 v[228:229], s[40:41], 0, v[132:133]
	global_load_lds_dwordx4 v[2:3], off
	v_lshl_add_u64 v[2:3], s[82:83], 0, v[138:139]
	s_add_i32 m0, s49, 0x2000
	v_lshl_add_u64 v[230:231], s[40:41], 0, v[136:137]
	global_load_lds_dwordx4 v[2:3], off
	s_mov_b32 m0, s57
	s_nop 0
	global_load_lds_dwordx4 v[228:229], off
	s_mov_b32 m0, s58
	s_nop 0
	global_load_lds_dwordx4 v[230:231], off
	s_waitcnt vmcnt(8)
	s_waitcnt lgkmcnt(0)
	s_barrier
; #define PG8_STAGE(bufoff, gbase, voff) do { _Pragma("unroll") for (int _i = 0; _i < 2; ++_i) \
;         __builtin_amdgcn_global_load_lds((const __attribute__((address_space(1))) unsigned*)((const char*)(gbase) + (voff)[_i]), (LAS unsigned*)(lds + (bufoff) + ldsw + _i * 8192), 16, 0, 0); } while (0)
; #define PG8_LDA(dst, b, h) do { _Pragma("unroll") for (int m = 0; m < 4; ++m) _Pragma("unroll") for (int k = 0; k < 2; ++k) dst[m][k] = *(const LAS bf16x8*)(lds + PG8_SA(b, h) + aoff + m * 2048 + k * 1024); } while (0)
; #define PG8_LDB(dst, b, h) do { _Pragma("unroll") for (int n = 0; n < 2; ++n) _Pragma("unroll") for (int k = 0; k < 2; ++k) dst[n][k] = *(const LAS bf16x8*)(lds + PG8_SB(b, h) + boff + n * 2048 + k * 1024); } while (0)
; #define PG8_MMA(ai, bj, At, Bt) do { __builtin_amdgcn_s_setprio(1); _Pragma("unroll") for (int m = 0; m < 4; ++m) _Pragma("unroll") for (int n = 0; n < 2; ++n) _Pragma("unroll") for (int k = 0; k < 2; ++k) \
;         acc[ai][bj][m][n] = __builtin_amdgcn_mfma_f32_16x16x32_bf16(Bt[n][k], At[m][k], acc[ai][bj][m][n], 0, 0, 0); __builtin_amdgcn_s_setprio(0); } while (0)
; #define PG8_WAIT_V(n) asm volatile("s_waitcnt vmcnt(" #n ")" ::: "memory")
; #define PG8_WAIT_L(n) asm volatile("s_waitcnt lgkmcnt(" #n ")" ::: "memory")
; #define PG8_BAR __builtin_amdgcn_s_barrier()
; #define PG8_SCHED __builtin_amdgcn_sched_barrier(0)
; template <class Epi, class SchedT, bool ALIGN_EPI, bool SP2>
; __device__ __forceinline__ void gemm_phase(LAS unsigned char* lds, const int ldk, const int nt, const SchedT& S, const Epi& E) {
;     ...
;             PG8_WAIT_V(8); PG8_WAIT_L(0); PG8_BAR; PG8_MMA(1, 0, At, B0); PG8_MMA(1, 1, At, B1); PG8_BAR; PG8_SCHED;
;             PG8_LDB(B0, 1, 0); PG8_LDB(B1, 1, 1); PG8_SCHED; PG8_LDA(At, 1, 0); PG8_STAGE(PG8_SA(0, 1), a2 + hstep, voffA);
;             PG8_WAIT_V(8); PG8_WAIT_L(0); PG8_BAR; PG8_MMA(0, 0, At, B0); PG8_MMA(0, 1, At, B1); PG8_BAR; PG8_SCHED;
	s_setprio 1
	s_waitcnt lgkmcnt(0)
	v_mfma_f32_16x16x32_bf16 v[64:67], v[144:147], v[194:197], v[64:67]
	v_mfma_f32_16x16x32_bf16 v[60:63], v[152:155], v[194:197], v[60:63]
	v_mfma_f32_16x16x32_bf16 v[52:55], v[152:155], v[202:205], v[52:55]
	v_mfma_f32_16x16x32_bf16 v[56:59], v[144:147], v[202:205], v[56:59]
	v_mfma_f32_16x16x32_bf16 v[48:51], v[144:147], v[210:213], v[48:51]
	v_mfma_f32_16x16x32_bf16 v[44:47], v[152:155], v[210:213], v[44:47]
	v_mfma_f32_16x16x32_bf16 v[36:39], v[152:155], v[218:221], v[36:39]
	v_mfma_f32_16x16x32_bf16 v[40:43], v[144:147], v[218:221], v[40:43]
	v_mfma_f32_16x16x32_bf16 v[64:67], v[148:151], v[198:201], v[64:67]
	v_mfma_f32_16x16x32_bf16 v[60:63], v[174:177], v[198:201], v[60:63]
	v_mfma_f32_16x16x32_bf16 v[52:55], v[174:177], v[206:209], v[52:55]
	v_mfma_f32_16x16x32_bf16 v[56:59], v[148:151], v[206:209], v[56:59]
	v_mfma_f32_16x16x32_bf16 v[48:51], v[148:151], v[214:217], v[48:51]
	v_mfma_f32_16x16x32_bf16 v[44:47], v[174:177], v[214:217], v[44:47]
	v_mfma_f32_16x16x32_bf16 v[36:39], v[174:177], v[222:225], v[36:39]
	v_mfma_f32_16x16x32_bf16 v[40:43], v[148:151], v[222:225], v[40:43]
	s_setprio 0
	s_setprio 1
	v_mfma_f32_16x16x32_bf16 v[32:35], v[178:181], v[194:197], v[32:35]
	v_mfma_f32_16x16x32_bf16 v[28:31], v[186:189], v[194:197], v[28:31]
	v_mfma_f32_16x16x32_bf16 v[20:23], v[186:189], v[202:205], v[20:23]
	v_mfma_f32_16x16x32_bf16 v[24:27], v[178:181], v[202:205], v[24:27]
	v_mfma_f32_16x16x32_bf16 v[16:19], v[178:181], v[210:213], v[16:19]
	v_mfma_f32_16x16x32_bf16 v[12:15], v[186:189], v[210:213], v[12:15]
	v_mfma_f32_16x16x32_bf16 v[2:5], v[186:189], v[218:221], v[4:7]
	v_mfma_f32_16x16x32_bf16 v[8:11], v[178:181], v[218:221], v[8:11]
	v_mfma_f32_16x16x32_bf16 v[32:35], v[182:185], v[198:201], v[32:35]
	v_mfma_f32_16x16x32_bf16 v[28:31], v[190:193], v[198:201], v[28:31]
	v_mfma_f32_16x16x32_bf16 v[20:23], v[190:193], v[206:209], v[20:23]
	v_mfma_f32_16x16x32_bf16 v[24:27], v[182:185], v[206:209], v[24:27]
	v_mfma_f32_16x16x32_bf16 v[16:19], v[182:185], v[214:217], v[16:19]
	v_mfma_f32_16x16x32_bf16 v[12:15], v[190:193], v[214:217], v[12:15]
	v_mfma_f32_16x16x32_bf16 v[2:5], v[190:193], v[222:225], v[2:5]
	v_mfma_f32_16x16x32_bf16 v[8:11], v[182:185], v[222:225], v[8:11]
	s_setprio 0
	s_barrier
	s_add_i32 s49, 0, 0x18000
	v_add_u32_e32 v0, s49, v159
	s_add_i32 s51, 0, 0x1c000
	ds_read_b128 v[144:147], v0
	ds_read_b128 v[148:151], v0 offset:1024
	ds_read_b128 v[152:155], v0 offset:2048
	ds_read_b128 v[174:177], v0 offset:3072
	v_add_u32_e32 v0, s51, v159
	ds_read_b128 v[178:181], v0
	ds_read_b128 v[182:185], v0 offset:1024
	ds_read_b128 v[186:189], v0 offset:2048
	ds_read_b128 v[190:193], v0 offset:3072
	s_add_u32 s40, s40, 0x80000
	s_addc_u32 s41, s41, 0
	s_mov_b32 m0, s59
	v_lshl_add_u64 v[6:7], s[40:41], 0, v[132:133]
	ds_read_b128 v[194:197], v161 offset:32768
	ds_read_b128 v[198:201], v161 offset:33792
	ds_read_b128 v[202:205], v161 offset:34816
	ds_read_b128 v[206:209], v161 offset:35840
	ds_read_b128 v[210:213], v161 offset:36864
	ds_read_b128 v[214:217], v161 offset:37888
	ds_read_b128 v[218:221], v161 offset:38912
	ds_read_b128 v[222:225], v161 offset:39936
	global_load_lds_dwordx4 v[6:7], off
	v_lshl_add_u64 v[6:7], s[40:41], 0, v[136:137]
	s_mov_b32 m0, s60
	s_nop 0
	global_load_lds_dwordx4 v[6:7], off
	s_waitcnt vmcnt(8)
	s_waitcnt lgkmcnt(0)
	s_barrier
	s_setprio 1
	s_waitcnt lgkmcnt(0)
	v_mfma_f32_16x16x32_bf16 v[128:131], v[144:147], v[194:197], v[128:131]
	v_mfma_f32_16x16x32_bf16 v[124:127], v[152:155], v[194:197], v[124:127]
	v_mfma_f32_16x16x32_bf16 v[116:119], v[152:155], v[202:205], v[116:119]
	v_mfma_f32_16x16x32_bf16 v[120:123], v[144:147], v[202:205], v[120:123]
	v_mfma_f32_16x16x32_bf16 v[112:115], v[144:147], v[210:213], v[112:115]
	v_mfma_f32_16x16x32_bf16 v[108:111], v[152:155], v[210:213], v[108:111]
	v_mfma_f32_16x16x32_bf16 v[100:103], v[152:155], v[218:221], v[100:103]
	v_mfma_f32_16x16x32_bf16 v[104:107], v[144:147], v[218:221], v[104:107]
	v_mfma_f32_16x16x32_bf16 v[128:131], v[148:151], v[198:201], v[128:131]
	v_mfma_f32_16x16x32_bf16 v[124:127], v[174:177], v[198:201], v[124:127]
	v_mfma_f32_16x16x32_bf16 v[116:119], v[174:177], v[206:209], v[116:119]
	v_mfma_f32_16x16x32_bf16 v[120:123], v[148:151], v[206:209], v[120:123]
	v_mfma_f32_16x16x32_bf16 v[112:115], v[148:151], v[214:217], v[112:115]
	v_mfma_f32_16x16x32_bf16 v[108:111], v[174:177], v[214:217], v[108:111]
	v_mfma_f32_16x16x32_bf16 v[100:103], v[174:177], v[222:225], v[100:103]
	v_mfma_f32_16x16x32_bf16 v[104:107], v[148:151], v[222:225], v[104:107]
	s_setprio 0
	s_setprio 1
	v_mfma_f32_16x16x32_bf16 v[96:99], v[178:181], v[194:197], v[96:99]
	v_mfma_f32_16x16x32_bf16 v[92:95], v[186:189], v[194:197], v[92:95]
	v_mfma_f32_16x16x32_bf16 v[84:87], v[186:189], v[202:205], v[84:87]
	v_mfma_f32_16x16x32_bf16 v[88:91], v[178:181], v[202:205], v[88:91]
	v_mfma_f32_16x16x32_bf16 v[80:83], v[178:181], v[210:213], v[80:83]
	v_mfma_f32_16x16x32_bf16 v[76:79], v[186:189], v[210:213], v[76:79]
	v_mfma_f32_16x16x32_bf16 v[68:71], v[186:189], v[218:221], v[68:71]
	v_mfma_f32_16x16x32_bf16 v[72:75], v[178:181], v[218:221], v[72:75]
	v_mfma_f32_16x16x32_bf16 v[96:99], v[182:185], v[198:201], v[96:99]
	v_mfma_f32_16x16x32_bf16 v[92:95], v[190:193], v[198:201], v[92:95]
	v_mfma_f32_16x16x32_bf16 v[84:87], v[190:193], v[206:209], v[84:87]
	v_mfma_f32_16x16x32_bf16 v[88:91], v[182:185], v[206:209], v[88:91]
	v_mfma_f32_16x16x32_bf16 v[80:83], v[182:185], v[214:217], v[80:83]
	v_mfma_f32_16x16x32_bf16 v[76:79], v[190:193], v[214:217], v[76:79]
	v_mfma_f32_16x16x32_bf16 v[68:71], v[190:193], v[222:225], v[68:71]
	v_mfma_f32_16x16x32_bf16 v[72:75], v[182:185], v[222:225], v[72:75]
	s_setprio 0
	s_barrier
; #define PG8_STAGE(bufoff, gbase, voff) do { _Pragma("unroll") for (int _i = 0; _i < 2; ++_i) \
;         __builtin_amdgcn_global_load_lds((const __attribute__((address_space(1))) unsigned*)((const char*)(gbase) + (voff)[_i]), (LAS unsigned*)(lds + (bufoff) + ldsw + _i * 8192), 16, 0, 0); } while (0)
; #define PG8_LDA(dst, b, h) do { _Pragma("unroll") for (int m = 0; m < 4; ++m) _Pragma("unroll") for (int k = 0; k < 2; ++k) dst[m][k] = *(const LAS bf16x8*)(lds + PG8_SA(b, h) + aoff + m * 2048 + k * 1024); } while (0)
; #define PG8_MMA(ai, bj, At, Bt) do { __builtin_amdgcn_s_setprio(1); _Pragma("unroll") for (int m = 0; m < 4; ++m) _Pragma("unroll") for (int n = 0; n < 2; ++n) _Pragma("unroll") for (int k = 0; k < 2; ++k) \
;         acc[ai][bj][m][n] = __builtin_amdgcn_mfma_f32_16x16x32_bf16(Bt[n][k], At[m][k], acc[ai][bj][m][n], 0, 0, 0); __builtin_amdgcn_s_setprio(0); } while (0)
; #define PG8_WAIT_V(n) asm volatile("s_waitcnt vmcnt(" #n ")" ::: "memory")
; #define PG8_WAIT_L(n) asm volatile("s_waitcnt lgkmcnt(" #n ")" ::: "memory")
; template <class Epi, class SchedT, bool ALIGN_EPI, bool SP2>
; __device__ __forceinline__ void gemm_phase(LAS unsigned char* lds, const int ldk, const int nt, const SchedT& S, const Epi& E) {
;     ...
;             PG8_LDA(At, 1, 1); PG8_STAGE(PG8_SB(1, 0), b3, voffB); PG8_STAGE(PG8_SB(1, 1), b3 + hstepB, voffB); PG8_STAGE(PG8_SA(1, 0), a3, voffA);
;             PG8_WAIT_V(8); PG8_WAIT_L(0); PG8_BAR; PG8_MMA(1, 0, At, B0); PG8_MMA(1, 1, At, B1); PG8_BAR; PG8_SCHED;
;     __device__ __forceinline__ void operator()(f32x4 (&acc)[2][2][4][2], const Unit& u, int wr, int wc, int fr, int fq) const {
;         const int row0 = u.pm * BM + wr * 64 + fr, col0 = u.pn * BM + wc * 64 + 8 * fq;
; #pragma unroll
;         for (int ai = 0; ai < 2; ++ai)
; #pragma unroll
;             for (int m = 0; m < 4; ++m) {
;                 const int row = row0 + ai * HALF + m * 16;
; #pragma unroll
;                 for (int bj = 0; bj < 2; ++bj) {
;                     const int col = col0 + bj * 32;
;                     const unsigned char* grow = (const unsigned char*)Gt + (size_t)row * 4096 + col;
;                     const u32x2 gw = *(const u32x2*)(grow + 2048);
;                     f32x4 g0 = gate_d4(gw.x), g1 = gate_d4(gw.y);
;                     if (u.kind == 0) {
;                         const u32x2 aw = *(const u32x2*)grow;
	s_add_i32 s40, s49, s56
	v_lshl_add_u64 v[6:7], v[156:157], 0, s[24:25]
	s_mov_b32 m0, s40
	ds_read_b128 v[194:197], v161 offset:49152
	ds_read_b128 v[198:201], v161 offset:50176
	ds_read_b128 v[202:205], v161 offset:51200
	ds_read_b128 v[206:209], v161 offset:52224
	ds_read_b128 v[210:213], v161 offset:53248
	ds_read_b128 v[214:217], v161 offset:54272
	ds_read_b128 v[218:221], v161 offset:55296
	ds_read_b128 v[222:225], v161 offset:56320
	global_load_lds_dwordx4 v[6:7], off
	s_add_i32 m0, s40, 0x2000
	s_add_u32 s36, s36, 0x20080
	v_lshl_add_u64 v[6:7], v[226:227], 0, s[24:25]
	s_addc_u32 s37, s37, 0
	s_add_i32 s40, s51, s56
	global_load_lds_dwordx4 v[6:7], off
	v_lshl_add_u64 v[6:7], s[36:37], 0, v[134:135]
	s_mov_b32 m0, s40
	s_nop 0
	global_load_lds_dwordx4 v[6:7], off
	v_lshl_add_u64 v[6:7], s[36:37], 0, v[138:139]
	s_add_i32 m0, s40, 0x2000
	s_nop 0
	global_load_lds_dwordx4 v[6:7], off
	v_lshl_add_u64 v[6:7], v[228:229], 0, s[24:25]
	s_mov_b32 m0, s61
	s_nop 0
	global_load_lds_dwordx4 v[6:7], off
	v_lshl_add_u64 v[6:7], v[230:231], 0, s[24:25]
	s_mov_b32 m0, s62
	s_nop 0
	global_load_lds_dwordx4 v[6:7], off
	s_waitcnt vmcnt(8)
	s_waitcnt lgkmcnt(0)
	s_barrier
	s_setprio 1
	s_waitcnt lgkmcnt(0)
	v_mfma_f32_16x16x32_bf16 v[64:67], v[144:147], v[194:197], v[64:67]
	v_mfma_f32_16x16x32_bf16 v[60:63], v[152:155], v[194:197], v[60:63]
	v_mfma_f32_16x16x32_bf16 v[52:55], v[152:155], v[202:205], v[52:55]
	v_mfma_f32_16x16x32_bf16 v[56:59], v[144:147], v[202:205], v[56:59]
	v_mfma_f32_16x16x32_bf16 v[48:51], v[144:147], v[210:213], v[48:51]
	v_mfma_f32_16x16x32_bf16 v[44:47], v[152:155], v[210:213], v[44:47]
	v_mfma_f32_16x16x32_bf16 v[36:39], v[152:155], v[218:221], v[36:39]
	v_mfma_f32_16x16x32_bf16 v[40:43], v[144:147], v[218:221], v[40:43]
	v_mfma_f32_16x16x32_bf16 v[64:67], v[148:151], v[198:201], v[64:67]
	v_mfma_f32_16x16x32_bf16 v[60:63], v[174:177], v[198:201], v[60:63]
	v_mfma_f32_16x16x32_bf16 v[52:55], v[174:177], v[206:209], v[52:55]
	v_mfma_f32_16x16x32_bf16 v[56:59], v[148:151], v[206:209], v[56:59]
	v_mfma_f32_16x16x32_bf16 v[48:51], v[148:151], v[214:217], v[48:51]
	v_mfma_f32_16x16x32_bf16 v[44:47], v[174:177], v[214:217], v[44:47]
	v_mfma_f32_16x16x32_bf16 v[36:39], v[174:177], v[222:225], v[36:39]
	v_mfma_f32_16x16x32_bf16 v[40:43], v[148:151], v[222:225], v[40:43]
	s_setprio 0
	s_setprio 1
	v_mfma_f32_16x16x32_bf16 v[32:35], v[178:181], v[194:197], v[32:35]
	v_mfma_f32_16x16x32_bf16 v[28:31], v[186:189], v[194:197], v[28:31]
	v_mfma_f32_16x16x32_bf16 v[20:23], v[186:189], v[202:205], v[20:23]
	v_mfma_f32_16x16x32_bf16 v[24:27], v[178:181], v[202:205], v[24:27]
	v_mfma_f32_16x16x32_bf16 v[16:19], v[178:181], v[210:213], v[16:19]
	v_mfma_f32_16x16x32_bf16 v[12:15], v[186:189], v[210:213], v[12:15]
	v_mfma_f32_16x16x32_bf16 v[2:5], v[186:189], v[218:221], v[2:5]
	v_mfma_f32_16x16x32_bf16 v[6:9], v[178:181], v[218:221], v[8:11]
	v_mfma_f32_16x16x32_bf16 v[32:35], v[182:185], v[198:201], v[32:35]
	v_mfma_f32_16x16x32_bf16 v[28:31], v[190:193], v[198:201], v[28:31]
	v_mfma_f32_16x16x32_bf16 v[20:23], v[190:193], v[206:209], v[20:23]
	v_mfma_f32_16x16x32_bf16 v[24:27], v[182:185], v[206:209], v[24:27]
	v_mfma_f32_16x16x32_bf16 v[16:19], v[182:185], v[214:217], v[16:19]
	v_mfma_f32_16x16x32_bf16 v[12:15], v[190:193], v[214:217], v[12:15]
	v_mfma_f32_16x16x32_bf16 v[8:11], v[182:185], v[222:225], v[6:9]
	v_mfma_f32_16x16x32_bf16 v[4:7], v[190:193], v[222:225], v[2:5]
	s_setprio 0
	s_barrier
	s_add_i32 s47, s47, 2
	s_add_u32 s34, s34, 0x100
	s_addc_u32 s35, s35, 0
	s_add_u32 s17, s17, 0x100
	s_addc_u32 s20, s20, 0
	s_cmp_gt_u32 s47, 13
	s_cbranch_scc0 .LBB0_534
	v_lshl_add_u32 v144, s16, 8, v158
	v_lshl_or_b32 v145, s12, 8, v160
	v_lshl_add_u32 v146, v144, 12, v145
	v_add_u32_e32 v147, 0x10000, v146
	v_add_u32_e32 v148, 0x20000, v146
	v_add_u32_e32 v149, 0x30000, v146
	v_add_u32_e32 v150, 0x80000, v146
	v_add_u32_e32 v151, 0x90000, v146
	v_add_u32_e32 v152, 0xa0000, v146
	v_add_u32_e32 v153, 0xb0000, v146
	s_cmp_lg_u32 s13, 0
	s_cbranch_scc1 .Lp3e_k1_loads
	global_load_dwordx2 v[174:175], v146, s[30:31] offset:2048
	global_load_dwordx2 v[176:177], v146, s[30:31] offset:0
	global_load_dwordx2 v[178:179], v146, s[30:31] offset:2080
	global_load_dwordx2 v[180:181], v146, s[30:31] offset:32
	global_load_dwordx2 v[182:183], v147, s[30:31] offset:2048
	global_load_dwordx2 v[184:185], v147, s[30:31] offset:0
	global_load_dwordx2 v[186:187], v147, s[30:31] offset:2080
	global_load_dwordx2 v[188:189], v147, s[30:31] offset:32
	global_load_dwordx2 v[190:191], v148, s[30:31] offset:2048
	global_load_dwordx2 v[192:193], v148, s[30:31] offset:0
	global_load_dwordx2 v[194:195], v148, s[30:31] offset:2080
	global_load_dwordx2 v[196:197], v148, s[30:31] offset:32
	global_load_dwordx2 v[198:199], v149, s[30:31] offset:2048
	global_load_dwordx2 v[200:201], v149, s[30:31] offset:0
	global_load_dwordx2 v[202:203], v149, s[30:31] offset:2080
	global_load_dwordx2 v[204:205], v149, s[30:31] offset:32
	global_load_dwordx2 v[206:207], v150, s[30:31] offset:2048
	global_load_dwordx2 v[208:209], v150, s[30:31] offset:0
	global_load_dwordx2 v[210:211], v150, s[30:31] offset:2080
	global_load_dwordx2 v[212:213], v150, s[30:31] offset:32
	global_load_dwordx2 v[214:215], v151, s[30:31] offset:2048
	global_load_dwordx2 v[216:217], v151, s[30:31] offset:0
	global_load_dwordx2 v[218:219], v151, s[30:31] offset:2080
	global_load_dwordx2 v[220:221], v151, s[30:31] offset:32
	global_load_dwordx2 v[222:223], v152, s[30:31] offset:2048
	global_load_dwordx2 v[224:225], v152, s[30:31] offset:0
	global_load_dwordx2 v[226:227], v152, s[30:31] offset:2080
	global_load_dwordx2 v[228:229], v152, s[30:31] offset:32
	global_load_dwordx2 v[230:231], v153, s[30:31] offset:2048
	global_load_dwordx2 v[232:233], v153, s[30:31] offset:0
	global_load_dwordx2 v[234:235], v153, s[30:31] offset:2080
	global_load_dwordx2 v[236:237], v153, s[30:31] offset:32
	s_branch .Lp3e_align

; #define PG8_STAGE(bufoff, gbase, voff) do { _Pragma("unroll") for (int _i = 0; _i < 2; ++_i) \
;         __builtin_amdgcn_global_load_lds((const __attribute__((address_space(1))) unsigned*)((const char*)(gbase) + (voff)[_i]), (LAS unsigned*)(lds + (bufoff) + ldsw + _i * 8192), 16, 0, 0); } while (0)
; #define PG8_LDA(dst, b, h) do { _Pragma("unroll") for (int m = 0; m < 4; ++m) _Pragma("unroll") for (int k = 0; k < 2; ++k) dst[m][k] = *(const LAS bf16x8*)(lds + PG8_SA(b, h) + aoff + m * 2048 + k * 1024); } while (0)
; #define PG8_LDB(dst, b, h) do { _Pragma("unroll") for (int n = 0; n < 2; ++n) _Pragma("unroll") for (int k = 0; k < 2; ++k) dst[n][k] = *(const LAS bf16x8*)(lds + PG8_SB(b, h) + boff + n * 2048 + k * 1024); } while (0)
; #define PG8_MMA(ai, bj, At, Bt) do { __builtin_amdgcn_s_setprio(1); _Pragma("unroll") for (int m = 0; m < 4; ++m) _Pragma("unroll") for (int n = 0; n < 2; ++n) _Pragma("unroll") for (int k = 0; k < 2; ++k) \
;         acc[ai][bj][m][n] = __builtin_amdgcn_mfma_f32_16x16x32_bf16(Bt[n][k], At[m][k], acc[ai][bj][m][n], 0, 0, 0); __builtin_amdgcn_s_setprio(0); } while (0)
; #define PG8_WAIT_V(n) asm volatile("s_waitcnt vmcnt(" #n ")" ::: "memory")
; #define PG8_WAIT_L(n) asm volatile("s_waitcnt lgkmcnt(" #n ")" ::: "memory")
; #define PG8_BAR __builtin_amdgcn_s_barrier()
; #define PG8_SCHED __builtin_amdgcn_sched_barrier(0)
; template <class Epi, class SchedT, bool ALIGN_EPI, bool SP2>
; __device__ __forceinline__ void gemm_phase(LAS unsigned char* lds, const int ldk, const int nt, const SchedT& S, const Epi& E) {
;     ...
;             const bool last = (t == nt - 2);
;             const char* a1 = cA + (size_t)(t + 1) * kstep;
;             const char* a2 = last ? nA : cA + (size_t)(t + 2) * kstep; const char* b2 = last ? nB : cB + (size_t)(t + 2) * kstep;
;             const char* a3 = a2 + kstep; const char* b3 = b2 + kstep;
;             if constexpr (SP2) {
;             PG8_LDB(B0, 0, 0); PG8_LDB(B1, 0, 1); PG8_SCHED; PG8_LDA(At, 0, 0); PG8_STAGE(PG8_SA(1, 1), a1 + hstep, voffA);
;             PG8_WAIT_V(8); PG8_WAIT_L(0); PG8_BAR; PG8_MMA(0, 0, At, B0); PG8_MMA(0, 1, At, B1); PG8_BAR; PG8_SCHED;
;             PG8_LDA(At, 0, 1); PG8_STAGE(PG8_SB(0, 0), b2, voffB); PG8_STAGE(PG8_SB(0, 1), b2 + hstepB, voffB); PG8_STAGE(PG8_SA(0, 0), a2, voffA);
.LBB0_668:
	s_add_u32 s36, s34, 0xfff80080
	s_addc_u32 s37, s35, -1
	s_add_i32 s51, 0, 0x10000
	s_cmp_eq_u32 s22, 28
	s_cselect_b32 s57, s1, s37
	s_cselect_b32 s56, s0, s36
	v_add_u32_e32 v144, s51, v147
	s_cselect_b32 s37, s55, s20
	s_cselect_b32 s36, s54, s13
	s_add_i32 s53, 0, 0x14000
	ds_read_b128 v[140:143], v144
	ds_read_b128 v[150:153], v144 offset:1024
	ds_read_b128 v[154:157], v144 offset:2048
	ds_read_b128 v[158:161], v144 offset:3072
	v_add_u32_e32 v144, s53, v147
	ds_read_b128 v[174:177], v144
	ds_read_b128 v[178:181], v144 offset:1024
	ds_read_b128 v[182:185], v144 offset:2048
	ds_read_b128 v[186:189], v144 offset:3072
	v_lshl_add_u64 v[144:145], s[34:35], 0, v[136:137]
	s_add_i32 m0, s17, 0xc000
	ds_read_b128 v[190:193], v149
	ds_read_b128 v[194:197], v149 offset:1024
	ds_read_b128 v[198:201], v149 offset:2048
	ds_read_b128 v[202:205], v149 offset:3072
	ds_read_b128 v[206:209], v149 offset:4096
	ds_read_b128 v[210:213], v149 offset:5120
	ds_read_b128 v[214:217], v149 offset:6144
	ds_read_b128 v[218:221], v149 offset:7168
	global_load_lds_dwordx4 v[144:145], off
	v_lshl_add_u64 v[144:145], s[34:35], 0, v[138:139]
	s_add_i32 m0, s17, 0xe000
	s_nop 0
	global_load_lds_dwordx4 v[144:145], off
	s_waitcnt vmcnt(8)
	s_waitcnt lgkmcnt(0)
	s_barrier
	s_setprio 1
	s_waitcnt lgkmcnt(0)
	v_mfma_f32_16x16x32_bf16 v[126:129], v[140:143], v[190:193], v[126:129]
	v_mfma_f32_16x16x32_bf16 v[122:125], v[154:157], v[190:193], v[122:125]
	v_mfma_f32_16x16x32_bf16 v[106:109], v[154:157], v[198:201], v[106:109]
	v_mfma_f32_16x16x32_bf16 v[110:113], v[140:143], v[198:201], v[110:113]
	v_mfma_f32_16x16x32_bf16 v[94:97], v[140:143], v[206:209], v[94:97]
	v_mfma_f32_16x16x32_bf16 v[90:93], v[154:157], v[206:209], v[90:93]
	v_mfma_f32_16x16x32_bf16 v[74:77], v[154:157], v[214:217], v[74:77]
	v_mfma_f32_16x16x32_bf16 v[78:81], v[140:143], v[214:217], v[78:81]
	v_mfma_f32_16x16x32_bf16 v[126:129], v[150:153], v[194:197], v[126:129]
	v_mfma_f32_16x16x32_bf16 v[122:125], v[158:161], v[194:197], v[122:125]
	v_mfma_f32_16x16x32_bf16 v[106:109], v[158:161], v[202:205], v[106:109]
	v_mfma_f32_16x16x32_bf16 v[110:113], v[150:153], v[202:205], v[110:113]
	v_mfma_f32_16x16x32_bf16 v[94:97], v[150:153], v[210:213], v[94:97]
	v_mfma_f32_16x16x32_bf16 v[90:93], v[158:161], v[210:213], v[90:93]
	v_mfma_f32_16x16x32_bf16 v[74:77], v[158:161], v[218:221], v[74:77]
	v_mfma_f32_16x16x32_bf16 v[78:81], v[150:153], v[218:221], v[78:81]
	s_setprio 0
	s_setprio 1
	v_mfma_f32_16x16x32_bf16 v[118:121], v[174:177], v[190:193], v[118:121]
	v_mfma_f32_16x16x32_bf16 v[114:117], v[182:185], v[190:193], v[114:117]
	v_mfma_f32_16x16x32_bf16 v[98:101], v[182:185], v[198:201], v[98:101]
	v_mfma_f32_16x16x32_bf16 v[102:105], v[174:177], v[198:201], v[102:105]
	v_mfma_f32_16x16x32_bf16 v[86:89], v[174:177], v[206:209], v[86:89]
	v_mfma_f32_16x16x32_bf16 v[82:85], v[182:185], v[206:209], v[82:85]
	v_mfma_f32_16x16x32_bf16 v[66:69], v[182:185], v[214:217], v[66:69]
	v_mfma_f32_16x16x32_bf16 v[70:73], v[174:177], v[214:217], v[70:73]
	v_mfma_f32_16x16x32_bf16 v[118:121], v[178:181], v[194:197], v[118:121]
	v_mfma_f32_16x16x32_bf16 v[114:117], v[186:189], v[194:197], v[114:117]
	v_mfma_f32_16x16x32_bf16 v[98:101], v[186:189], v[202:205], v[98:101]
	v_mfma_f32_16x16x32_bf16 v[102:105], v[178:181], v[202:205], v[102:105]
	v_mfma_f32_16x16x32_bf16 v[86:89], v[178:181], v[210:213], v[86:89]
	v_mfma_f32_16x16x32_bf16 v[82:85], v[186:189], v[210:213], v[82:85]
	v_mfma_f32_16x16x32_bf16 v[66:69], v[186:189], v[218:221], v[66:69]
	v_mfma_f32_16x16x32_bf16 v[70:73], v[178:181], v[218:221], v[70:73]
	s_setprio 0
	s_barrier
	s_add_i32 s51, s51, s61
	v_lshl_add_u64 v[144:145], s[36:37], 0, v[0:1]
	s_mov_b32 m0, s51
	ds_read_b128 v[190:193], v149 offset:16384
	ds_read_b128 v[194:197], v149 offset:17408
	ds_read_b128 v[198:201], v149 offset:18432
	ds_read_b128 v[202:205], v149 offset:19456
	ds_read_b128 v[206:209], v149 offset:20480
	ds_read_b128 v[210:213], v149 offset:21504
	ds_read_b128 v[214:217], v149 offset:22528
	ds_read_b128 v[218:221], v149 offset:23552
	global_load_lds_dwordx4 v[144:145], off
	s_add_i32 m0, s51, 0x2000
	s_add_u32 s86, s36, 0x20000
	v_lshl_add_u64 v[222:223], s[36:37], 0, v[134:135]
	s_addc_u32 s87, s37, 0
	s_add_i32 s51, s53, s61
	global_load_lds_dwordx4 v[222:223], off
	v_lshl_add_u64 v[224:225], s[86:87], 0, v[0:1]
	s_mov_b32 m0, s51
	v_lshl_add_u64 v[226:227], s[56:57], 0, v[132:133]
	global_load_lds_dwordx4 v[224:225], off
	v_lshl_add_u64 v[224:225], s[86:87], 0, v[134:135]
	s_add_i32 m0, s51, 0x2000
	s_nop 0
	global_load_lds_dwordx4 v[224:225], off
	v_lshl_add_u64 v[224:225], s[56:57], 0, v[130:131]
	s_mov_b32 m0, s17
	s_nop 0
	global_load_lds_dwordx4 v[224:225], off
	s_mov_b32 m0, s62
	s_nop 0
	global_load_lds_dwordx4 v[226:227], off
	s_waitcnt vmcnt(8)
	s_waitcnt lgkmcnt(0)
	s_barrier
; #define PG8_STAGE(bufoff, gbase, voff) do { _Pragma("unroll") for (int _i = 0; _i < 2; ++_i) \
;         __builtin_amdgcn_global_load_lds((const __attribute__((address_space(1))) unsigned*)((const char*)(gbase) + (voff)[_i]), (LAS unsigned*)(lds + (bufoff) + ldsw + _i * 8192), 16, 0, 0); } while (0)
; #define PG8_LDA(dst, b, h) do { _Pragma("unroll") for (int m = 0; m < 4; ++m) _Pragma("unroll") for (int k = 0; k < 2; ++k) dst[m][k] = *(const LAS bf16x8*)(lds + PG8_SA(b, h) + aoff + m * 2048 + k * 1024); } while (0)
; #define PG8_LDB(dst, b, h) do { _Pragma("unroll") for (int n = 0; n < 2; ++n) _Pragma("unroll") for (int k = 0; k < 2; ++k) dst[n][k] = *(const LAS bf16x8*)(lds + PG8_SB(b, h) + boff + n * 2048 + k * 1024); } while (0)
; #define PG8_MMA(ai, bj, At, Bt) do { __builtin_amdgcn_s_setprio(1); _Pragma("unroll") for (int m = 0; m < 4; ++m) _Pragma("unroll") for (int n = 0; n < 2; ++n) _Pragma("unroll") for (int k = 0; k < 2; ++k) \
;         acc[ai][bj][m][n] = __builtin_amdgcn_mfma_f32_16x16x32_bf16(Bt[n][k], At[m][k], acc[ai][bj][m][n], 0, 0, 0); __builtin_amdgcn_s_setprio(0); } while (0)
; #define PG8_WAIT_V(n) asm volatile("s_waitcnt vmcnt(" #n ")" ::: "memory")
; #define PG8_WAIT_L(n) asm volatile("s_waitcnt lgkmcnt(" #n ")" ::: "memory")
; #define PG8_BAR __builtin_amdgcn_s_barrier()
; #define PG8_SCHED __builtin_amdgcn_sched_barrier(0)
; template <class Epi, class SchedT, bool ALIGN_EPI, bool SP2>
; __device__ __forceinline__ void gemm_phase(LAS unsigned char* lds, const int ldk, const int nt, const SchedT& S, const Epi& E) {
;     ...
;             PG8_WAIT_V(8); PG8_WAIT_L(0); PG8_BAR; PG8_MMA(1, 0, At, B0); PG8_MMA(1, 1, At, B1); PG8_BAR; PG8_SCHED;
;             PG8_LDB(B0, 1, 0); PG8_LDB(B1, 1, 1); PG8_SCHED; PG8_LDA(At, 1, 0); PG8_STAGE(PG8_SA(0, 1), a2 + hstep, voffA);
;             PG8_WAIT_V(8); PG8_WAIT_L(0); PG8_BAR; PG8_MMA(0, 0, At, B0); PG8_MMA(0, 1, At, B1); PG8_BAR; PG8_SCHED;
	s_setprio 1
	s_waitcnt lgkmcnt(0)
	v_mfma_f32_16x16x32_bf16 v[62:65], v[140:143], v[190:193], v[62:65]
	v_mfma_f32_16x16x32_bf16 v[58:61], v[154:157], v[190:193], v[58:61]
	v_mfma_f32_16x16x32_bf16 v[42:45], v[154:157], v[198:201], v[42:45]
	v_mfma_f32_16x16x32_bf16 v[46:49], v[140:143], v[198:201], v[46:49]
	v_mfma_f32_16x16x32_bf16 v[30:33], v[140:143], v[206:209], v[30:33]
	v_mfma_f32_16x16x32_bf16 v[26:29], v[154:157], v[206:209], v[26:29]
	v_mfma_f32_16x16x32_bf16 v[10:13], v[154:157], v[214:217], v[10:13]
	v_mfma_f32_16x16x32_bf16 v[14:17], v[140:143], v[214:217], v[14:17]
	v_mfma_f32_16x16x32_bf16 v[62:65], v[150:153], v[194:197], v[62:65]
	v_mfma_f32_16x16x32_bf16 v[58:61], v[158:161], v[194:197], v[58:61]
	v_mfma_f32_16x16x32_bf16 v[42:45], v[158:161], v[202:205], v[42:45]
	v_mfma_f32_16x16x32_bf16 v[46:49], v[150:153], v[202:205], v[46:49]
	v_mfma_f32_16x16x32_bf16 v[30:33], v[150:153], v[210:213], v[30:33]
	v_mfma_f32_16x16x32_bf16 v[26:29], v[158:161], v[210:213], v[26:29]
	v_mfma_f32_16x16x32_bf16 v[10:13], v[158:161], v[218:221], v[10:13]
	v_mfma_f32_16x16x32_bf16 v[14:17], v[150:153], v[218:221], v[14:17]
	s_setprio 0
	s_setprio 1
	v_mfma_f32_16x16x32_bf16 v[54:57], v[174:177], v[190:193], v[54:57]
	v_mfma_f32_16x16x32_bf16 v[50:53], v[182:185], v[190:193], v[50:53]
	v_mfma_f32_16x16x32_bf16 v[34:37], v[182:185], v[198:201], v[34:37]
	v_mfma_f32_16x16x32_bf16 v[38:41], v[174:177], v[198:201], v[38:41]
	v_mfma_f32_16x16x32_bf16 v[22:25], v[174:177], v[206:209], v[22:25]
	v_mfma_f32_16x16x32_bf16 v[18:21], v[182:185], v[206:209], v[18:21]
	v_mfma_f32_16x16x32_bf16 v[2:5], v[182:185], v[214:217], v[2:5]
	v_mfma_f32_16x16x32_bf16 v[6:9], v[174:177], v[214:217], v[6:9]
	v_mfma_f32_16x16x32_bf16 v[54:57], v[178:181], v[194:197], v[54:57]
	v_mfma_f32_16x16x32_bf16 v[50:53], v[186:189], v[194:197], v[50:53]
	v_mfma_f32_16x16x32_bf16 v[34:37], v[186:189], v[202:205], v[34:37]
	v_mfma_f32_16x16x32_bf16 v[38:41], v[178:181], v[202:205], v[38:41]
	v_mfma_f32_16x16x32_bf16 v[22:25], v[178:181], v[210:213], v[22:25]
	v_mfma_f32_16x16x32_bf16 v[18:21], v[186:189], v[210:213], v[18:21]
	v_mfma_f32_16x16x32_bf16 v[2:5], v[186:189], v[218:221], v[2:5]
	v_mfma_f32_16x16x32_bf16 v[6:9], v[178:181], v[218:221], v[6:9]
	s_setprio 0
	s_barrier
	s_add_i32 s51, 0, 0x18000
	s_add_i32 s53, 0, 0x1c000
	v_add_u32_e32 v158, s51, v147
	v_add_u32_e32 v186, s53, v147
	ds_read_b128 v[140:143], v158
	ds_read_b128 v[150:153], v158 offset:1024
	ds_read_b128 v[154:157], v158 offset:2048
	ds_read_b128 v[158:161], v158 offset:3072
	ds_read_b128 v[174:177], v186
	ds_read_b128 v[178:181], v186 offset:1024
	ds_read_b128 v[182:185], v186 offset:2048
	ds_read_b128 v[186:189], v186 offset:3072
	s_add_u32 s56, s56, 0x80000
	s_addc_u32 s57, s57, 0
	s_mov_b32 m0, s63
	v_lshl_add_u64 v[228:229], s[56:57], 0, v[130:131]
	ds_read_b128 v[190:193], v149 offset:32768
	ds_read_b128 v[194:197], v149 offset:33792
	ds_read_b128 v[198:201], v149 offset:34816
	ds_read_b128 v[202:205], v149 offset:35840
	ds_read_b128 v[206:209], v149 offset:36864
	ds_read_b128 v[210:213], v149 offset:37888
	ds_read_b128 v[214:217], v149 offset:38912
	ds_read_b128 v[218:221], v149 offset:39936
	global_load_lds_dwordx4 v[228:229], off
	v_lshl_add_u64 v[228:229], s[56:57], 0, v[132:133]
	s_mov_b32 m0, s81
	s_nop 0
	global_load_lds_dwordx4 v[228:229], off
	s_waitcnt vmcnt(8)
	s_waitcnt lgkmcnt(0)
	s_barrier
	s_setprio 1
	s_waitcnt lgkmcnt(0)
	v_mfma_f32_16x16x32_bf16 v[126:129], v[140:143], v[190:193], v[126:129]
	v_mfma_f32_16x16x32_bf16 v[122:125], v[154:157], v[190:193], v[122:125]
	v_mfma_f32_16x16x32_bf16 v[106:109], v[154:157], v[198:201], v[106:109]
	v_mfma_f32_16x16x32_bf16 v[110:113], v[140:143], v[198:201], v[110:113]
	v_mfma_f32_16x16x32_bf16 v[94:97], v[140:143], v[206:209], v[94:97]
	v_mfma_f32_16x16x32_bf16 v[90:93], v[154:157], v[206:209], v[90:93]
	v_mfma_f32_16x16x32_bf16 v[74:77], v[154:157], v[214:217], v[74:77]
	v_mfma_f32_16x16x32_bf16 v[78:81], v[140:143], v[214:217], v[78:81]
	v_mfma_f32_16x16x32_bf16 v[126:129], v[150:153], v[194:197], v[126:129]
	v_mfma_f32_16x16x32_bf16 v[122:125], v[158:161], v[194:197], v[122:125]
	v_mfma_f32_16x16x32_bf16 v[106:109], v[158:161], v[202:205], v[106:109]
	v_mfma_f32_16x16x32_bf16 v[110:113], v[150:153], v[202:205], v[110:113]
	v_mfma_f32_16x16x32_bf16 v[94:97], v[150:153], v[210:213], v[94:97]
	v_mfma_f32_16x16x32_bf16 v[90:93], v[158:161], v[210:213], v[90:93]
	v_mfma_f32_16x16x32_bf16 v[74:77], v[158:161], v[218:221], v[74:77]
	v_mfma_f32_16x16x32_bf16 v[78:81], v[150:153], v[218:221], v[78:81]
	s_setprio 0
	s_setprio 1
	v_mfma_f32_16x16x32_bf16 v[118:121], v[174:177], v[190:193], v[118:121]
	v_mfma_f32_16x16x32_bf16 v[114:117], v[182:185], v[190:193], v[114:117]
	v_mfma_f32_16x16x32_bf16 v[98:101], v[182:185], v[198:201], v[98:101]
	v_mfma_f32_16x16x32_bf16 v[102:105], v[174:177], v[198:201], v[102:105]
	v_mfma_f32_16x16x32_bf16 v[86:89], v[174:177], v[206:209], v[86:89]
	v_mfma_f32_16x16x32_bf16 v[82:85], v[182:185], v[206:209], v[82:85]
	v_mfma_f32_16x16x32_bf16 v[66:69], v[182:185], v[214:217], v[66:69]
	v_mfma_f32_16x16x32_bf16 v[70:73], v[174:177], v[214:217], v[70:73]
	v_mfma_f32_16x16x32_bf16 v[118:121], v[178:181], v[194:197], v[118:121]
	v_mfma_f32_16x16x32_bf16 v[114:117], v[186:189], v[194:197], v[114:117]
	v_mfma_f32_16x16x32_bf16 v[98:101], v[186:189], v[202:205], v[98:101]
	v_mfma_f32_16x16x32_bf16 v[102:105], v[178:181], v[202:205], v[102:105]
	v_mfma_f32_16x16x32_bf16 v[86:89], v[178:181], v[210:213], v[86:89]
	v_mfma_f32_16x16x32_bf16 v[82:85], v[186:189], v[210:213], v[82:85]
	v_mfma_f32_16x16x32_bf16 v[66:69], v[186:189], v[218:221], v[66:69]
	v_mfma_f32_16x16x32_bf16 v[70:73], v[178:181], v[218:221], v[70:73]
	s_setprio 0
	s_barrier
; #define PG8_STAGE(bufoff, gbase, voff) do { _Pragma("unroll") for (int _i = 0; _i < 2; ++_i) \
;         __builtin_amdgcn_global_load_lds((const __attribute__((address_space(1))) unsigned*)((const char*)(gbase) + (voff)[_i]), (LAS unsigned*)(lds + (bufoff) + ldsw + _i * 8192), 16, 0, 0); } while (0)
; #define PG8_LDA(dst, b, h) do { _Pragma("unroll") for (int m = 0; m < 4; ++m) _Pragma("unroll") for (int k = 0; k < 2; ++k) dst[m][k] = *(const LAS bf16x8*)(lds + PG8_SA(b, h) + aoff + m * 2048 + k * 1024); } while (0)
; #define PG8_MMA(ai, bj, At, Bt) do { __builtin_amdgcn_s_setprio(1); _Pragma("unroll") for (int m = 0; m < 4; ++m) _Pragma("unroll") for (int n = 0; n < 2; ++n) _Pragma("unroll") for (int k = 0; k < 2; ++k) \
;         acc[ai][bj][m][n] = __builtin_amdgcn_mfma_f32_16x16x32_bf16(Bt[n][k], At[m][k], acc[ai][bj][m][n], 0, 0, 0); __builtin_amdgcn_s_setprio(0); } while (0)
; #define PG8_WAIT_V(n) asm volatile("s_waitcnt vmcnt(" #n ")" ::: "memory")
; #define PG8_WAIT_L(n) asm volatile("s_waitcnt lgkmcnt(" #n ")" ::: "memory")
; #define PG8_BAR __builtin_amdgcn_s_barrier()
; #define PG8_SCHED __builtin_amdgcn_sched_barrier(0)
; template <class Epi, class SchedT, bool ALIGN_EPI, bool SP2>
; __device__ __forceinline__ void gemm_phase(LAS unsigned char* lds, const int ldk, const int nt, const SchedT& S, const Epi& E) {
;     ...
;             PG8_LDA(At, 1, 1); PG8_STAGE(PG8_SB(1, 0), b3, voffB); PG8_STAGE(PG8_SB(1, 1), b3 + hstepB, voffB); PG8_STAGE(PG8_SA(1, 0), a3, voffA);
;             PG8_WAIT_V(8); PG8_WAIT_L(0); PG8_BAR; PG8_MMA(1, 0, At, B0); PG8_MMA(1, 1, At, B1); PG8_BAR; PG8_SCHED;
;     __device__ __forceinline__ void operator()(f32x4 (&acc)[2][2][4][2], const Unit& u, int wr, int wc, int fr, int fq) const {
;         const int row0 = u.pm * BM + wr * 64 + fr, col0 = u.pn * BM + wc * 64 + 8 * fq;
; #pragma unroll
;         for (int ai = 0; ai < 2; ++ai)
; #pragma unroll
;             for (int m = 0; m < 4; ++m) {
;                 const int row = row0 + ai * HALF + m * 16; float sq = 0.f;
; #pragma unroll
;                 for (int bj = 0; bj < 2; ++bj) {
;                     const size_t off = (size_t)row * D + col0 + bj * 32;
;                     const u32x4 xw = *(const u32x4*)(xin + off);
	s_add_i32 s51, s51, s61
	v_lshl_add_u64 v[144:145], v[144:145], 0, s[24:25]
	s_mov_b32 m0, s51
	ds_read_b128 v[190:193], v149 offset:49152
	ds_read_b128 v[194:197], v149 offset:50176
	ds_read_b128 v[198:201], v149 offset:51200
	ds_read_b128 v[202:205], v149 offset:52224
	ds_read_b128 v[206:209], v149 offset:53248
	ds_read_b128 v[210:213], v149 offset:54272
	ds_read_b128 v[214:217], v149 offset:55296
	ds_read_b128 v[218:221], v149 offset:56320
	global_load_lds_dwordx4 v[144:145], off
	s_add_i32 m0, s51, 0x2000
	s_add_u32 s36, s36, 0x20080
	v_lshl_add_u64 v[144:145], v[222:223], 0, s[24:25]
	s_addc_u32 s37, s37, 0
	s_add_i32 s51, s53, s61
	global_load_lds_dwordx4 v[144:145], off
	v_lshl_add_u64 v[144:145], s[36:37], 0, v[0:1]
	s_mov_b32 m0, s51
	s_nop 0
	global_load_lds_dwordx4 v[144:145], off
	v_lshl_add_u64 v[144:145], s[36:37], 0, v[134:135]
	s_add_i32 m0, s51, 0x2000
	s_nop 0
	global_load_lds_dwordx4 v[144:145], off
	v_lshl_add_u64 v[144:145], v[224:225], 0, s[24:25]
	s_mov_b32 m0, s83
	s_nop 0
	global_load_lds_dwordx4 v[144:145], off
	v_lshl_add_u64 v[144:145], v[226:227], 0, s[24:25]
	s_mov_b32 m0, s84
	s_nop 0
	global_load_lds_dwordx4 v[144:145], off
	s_waitcnt vmcnt(8)
	s_waitcnt lgkmcnt(0)
	s_barrier
	s_setprio 1
	s_waitcnt lgkmcnt(0)
	v_mfma_f32_16x16x32_bf16 v[62:65], v[140:143], v[190:193], v[62:65]
	v_mfma_f32_16x16x32_bf16 v[58:61], v[154:157], v[190:193], v[58:61]
	v_mfma_f32_16x16x32_bf16 v[42:45], v[154:157], v[198:201], v[42:45]
	v_mfma_f32_16x16x32_bf16 v[46:49], v[140:143], v[198:201], v[46:49]
	v_mfma_f32_16x16x32_bf16 v[30:33], v[140:143], v[206:209], v[30:33]
	v_mfma_f32_16x16x32_bf16 v[26:29], v[154:157], v[206:209], v[26:29]
	v_mfma_f32_16x16x32_bf16 v[10:13], v[154:157], v[214:217], v[10:13]
	v_mfma_f32_16x16x32_bf16 v[14:17], v[140:143], v[214:217], v[14:17]
	v_mfma_f32_16x16x32_bf16 v[62:65], v[150:153], v[194:197], v[62:65]
	v_mfma_f32_16x16x32_bf16 v[58:61], v[158:161], v[194:197], v[58:61]
	v_mfma_f32_16x16x32_bf16 v[42:45], v[158:161], v[202:205], v[42:45]
	v_mfma_f32_16x16x32_bf16 v[46:49], v[150:153], v[202:205], v[46:49]
	v_mfma_f32_16x16x32_bf16 v[30:33], v[150:153], v[210:213], v[30:33]
	v_mfma_f32_16x16x32_bf16 v[26:29], v[158:161], v[210:213], v[26:29]
	v_mfma_f32_16x16x32_bf16 v[10:13], v[158:161], v[218:221], v[10:13]
	v_mfma_f32_16x16x32_bf16 v[14:17], v[150:153], v[218:221], v[14:17]
	s_setprio 0
	s_setprio 1
	v_mfma_f32_16x16x32_bf16 v[54:57], v[174:177], v[190:193], v[54:57]
	v_mfma_f32_16x16x32_bf16 v[50:53], v[182:185], v[190:193], v[50:53]
	v_mfma_f32_16x16x32_bf16 v[34:37], v[182:185], v[198:201], v[34:37]
	v_mfma_f32_16x16x32_bf16 v[38:41], v[174:177], v[198:201], v[38:41]
	v_mfma_f32_16x16x32_bf16 v[22:25], v[174:177], v[206:209], v[22:25]
	v_mfma_f32_16x16x32_bf16 v[18:21], v[182:185], v[206:209], v[18:21]
	v_mfma_f32_16x16x32_bf16 v[2:5], v[182:185], v[214:217], v[2:5]
	v_mfma_f32_16x16x32_bf16 v[6:9], v[174:177], v[214:217], v[6:9]
	v_mfma_f32_16x16x32_bf16 v[54:57], v[178:181], v[194:197], v[54:57]
	v_mfma_f32_16x16x32_bf16 v[50:53], v[186:189], v[194:197], v[50:53]
	v_mfma_f32_16x16x32_bf16 v[34:37], v[186:189], v[202:205], v[34:37]
	v_mfma_f32_16x16x32_bf16 v[38:41], v[178:181], v[202:205], v[38:41]
	v_mfma_f32_16x16x32_bf16 v[22:25], v[178:181], v[210:213], v[22:25]
	v_mfma_f32_16x16x32_bf16 v[18:21], v[186:189], v[210:213], v[18:21]
	v_mfma_f32_16x16x32_bf16 v[2:5], v[186:189], v[218:221], v[2:5]
	v_mfma_f32_16x16x32_bf16 v[6:9], v[178:181], v[218:221], v[6:9]
	s_setprio 0
	s_barrier
	s_add_i32 s22, s22, 2
	s_add_u32 s34, s34, 0x100
	s_addc_u32 s35, s35, 0
	s_add_u32 s13, s13, 0x100
	s_addc_u32 s20, s20, 0
	s_cmp_gt_u32 s22, 29
	s_cbranch_scc0 .LBB0_668
	v_lshl_add_u32 v142, s16, 8, v146
	v_lshl_or_b32 v140, s12, 8, v148
	v_lshlrev_b32_e32 v141, 12, v142
	v_lshl_add_u32 v150, v140, 1, v141
	v_add_u32_e32 v151, 0x10000, v150
	v_add_u32_e32 v152, 0x20000, v150
	v_add_u32_e32 v153, 0x30000, v150
	v_add_u32_e32 v154, 0x80000, v150
	v_add_u32_e32 v155, 0x90000, v150
	v_add_u32_e32 v156, 0xa0000, v150
	v_add_u32_e32 v157, 0xb0000, v150
	global_load_dwordx4 v[174:177], v150, s[42:43]
	global_load_dwordx4 v[178:181], v150, s[42:43] offset:64
	global_load_dwordx4 v[182:185], v151, s[42:43]
	global_load_dwordx4 v[186:189], v151, s[42:43] offset:64
	global_load_dwordx4 v[190:193], v152, s[42:43]
	global_load_dwordx4 v[194:197], v152, s[42:43] offset:64
	global_load_dwordx4 v[198:201], v153, s[42:43]
	global_load_dwordx4 v[202:205], v153, s[42:43] offset:64
	global_load_dwordx4 v[206:209], v154, s[42:43]
	global_load_dwordx4 v[210:213], v154, s[42:43] offset:64
	global_load_dwordx4 v[214:217], v155, s[42:43]
	global_load_dwordx4 v[218:221], v155, s[42:43] offset:64
	global_load_dwordx4 v[222:225], v156, s[42:43]
	global_load_dwordx4 v[226:229], v156, s[42:43] offset:64
	global_load_dwordx4 v[230:233], v157, s[42:43]
	global_load_dwordx4 v[234:237], v157, s[42:43] offset:64
	s_lshl_b32 s56, s12, 4
	s_lshl_b32 s22, s82, 2
	s_add_i32 s56, s56, s22
	v_lshl_add_u32 v158, v142, 7, s56
	v_add_u32_e32 v159, 0x1000, v158
	v_add_u32_e32 v160, 0x4000, v158
	v_add_u32_e32 v161, 0x5000, v158
	v_xor_b32_e32 v239, 16, v241
	v_xor_b32_e32 v252, 32, v241
	v_lshlrev_b32_e32 v239, 2, v239
	v_lshlrev_b32_e32 v252, 2, v252
	s_and_b64 vcc, exec, s[48:49]
	s_cbranch_vccz .LBB0_671
	s_barrier

; #define PG8_STAGE(bufoff, gbase, voff) do { _Pragma("unroll") for (int _i = 0; _i < 2; ++_i) \
;         __builtin_amdgcn_global_load_lds((const __attribute__((address_space(1))) unsigned*)((const char*)(gbase) + (voff)[_i]), (LAS unsigned*)(lds + (bufoff) + ldsw + _i * 8192), 16, 0, 0); } while (0)
; #define PG8_LDA(dst, b, h) do { _Pragma("unroll") for (int m = 0; m < 4; ++m) _Pragma("unroll") for (int k = 0; k < 2; ++k) dst[m][k] = *(const LAS bf16x8*)(lds + PG8_SA(b, h) + aoff + m * 2048 + k * 1024); } while (0)
; #define PG8_LDB(dst, b, h) do { _Pragma("unroll") for (int n = 0; n < 2; ++n) _Pragma("unroll") for (int k = 0; k < 2; ++k) dst[n][k] = *(const LAS bf16x8*)(lds + PG8_SB(b, h) + boff + n * 2048 + k * 1024); } while (0)
; #define PG8_MMA(ai, bj, At, Bt) do { __builtin_amdgcn_s_setprio(1); _Pragma("unroll") for (int m = 0; m < 4; ++m) _Pragma("unroll") for (int n = 0; n < 2; ++n) _Pragma("unroll") for (int k = 0; k < 2; ++k) \
;         acc[ai][bj][m][n] = __builtin_amdgcn_mfma_f32_16x16x32_bf16(Bt[n][k], At[m][k], acc[ai][bj][m][n], 0, 0, 0); __builtin_amdgcn_s_setprio(0); } while (0)
; #define PG8_WAIT_V(n) asm volatile("s_waitcnt vmcnt(" #n ")" ::: "memory")
; #define PG8_WAIT_L(n) asm volatile("s_waitcnt lgkmcnt(" #n ")" ::: "memory")
; #define PG8_BAR __builtin_amdgcn_s_barrier()
; #define PG8_SCHED __builtin_amdgcn_sched_barrier(0)
; template <class Epi, class SchedT, bool ALIGN_EPI, bool SP2>
; __device__ __forceinline__ void gemm_phase(LAS unsigned char* lds, const int ldk, const int nt, const SchedT& S, const Epi& E) {
;     ...
;             const bool last = (t == nt - 2);
;             const char* a1 = cA + (size_t)(t + 1) * kstep;
;             const char* a2 = last ? nA : cA + (size_t)(t + 2) * kstep; const char* b2 = last ? nB : cB + (size_t)(t + 2) * kstep;
;             const char* a3 = a2 + kstep; const char* b3 = b2 + kstep;
;             if constexpr (SP2) {
;             PG8_LDB(B0, 0, 0); PG8_LDB(B1, 0, 1); PG8_SCHED; PG8_LDA(At, 0, 0); PG8_STAGE(PG8_SA(1, 1), a1 + hstep, voffA);
;             PG8_WAIT_V(8); PG8_WAIT_L(0); PG8_BAR; PG8_MMA(0, 0, At, B0); PG8_MMA(0, 1, At, B1); PG8_BAR; PG8_SCHED;
;             PG8_LDA(At, 0, 1); PG8_STAGE(PG8_SB(0, 0), b2, voffB); PG8_STAGE(PG8_SB(0, 1), b2 + hstepB, voffB); PG8_STAGE(PG8_SA(0, 0), a2, voffA);
.LBB0_752:
	s_add_u32 s36, s34, 0xfff80080
	s_addc_u32 s37, s35, -1
	s_add_i32 s61, 0, 0x10000
	s_cmp_eq_u32 s59, 28
	s_cselect_b32 vcc_hi, s1, s37
	s_cselect_b32 vcc_lo, s0, s36
	s_cselect_b32 s37, s63, s17
	s_cselect_b32 s36, s62, s13
	s_add_i32 s64, 0, 0x14000
	v_add_u32_e32 v142, s61, v248
	v_add_u32_e32 v182, s64, v248
	ds_read_b128 v[130:133], v142
	ds_read_b128 v[134:137], v142 offset:1024
	ds_read_b128 v[138:141], v142 offset:2048
	ds_read_b128 v[142:145], v142 offset:3072
	ds_read_b128 v[158:161], v182
	ds_read_b128 v[174:177], v182 offset:1024
	ds_read_b128 v[178:181], v182 offset:2048
	ds_read_b128 v[182:185], v182 offset:3072
	v_lshl_add_u64 v[218:219], s[34:35], 0, v[154:155]
	s_add_i32 m0, s85, 0xc000
	ds_read_b128 v[186:189], v251
	ds_read_b128 v[190:193], v251 offset:1024
	ds_read_b128 v[194:197], v251 offset:2048
	ds_read_b128 v[198:201], v251 offset:3072
	ds_read_b128 v[202:205], v251 offset:4096
	ds_read_b128 v[206:209], v251 offset:5120
	ds_read_b128 v[210:213], v251 offset:6144
	ds_read_b128 v[214:217], v251 offset:7168
	global_load_lds_dwordx4 v[218:219], off
	v_lshl_add_u64 v[218:219], s[34:35], 0, v[156:157]
	s_add_i32 m0, s85, 0xe000
	s_nop 0
	global_load_lds_dwordx4 v[218:219], off
	s_waitcnt vmcnt(8)
	s_waitcnt lgkmcnt(0)
	s_barrier
	s_setprio 1
	s_waitcnt lgkmcnt(0)
	v_mfma_f32_16x16x32_bf16 v[126:129], v[130:133], v[186:189], v[126:129]
	v_mfma_f32_16x16x32_bf16 v[62:65], v[138:141], v[186:189], v[62:65]
	v_mfma_f32_16x16x32_bf16 v[58:61], v[138:141], v[194:197], v[58:61]
	v_mfma_f32_16x16x32_bf16 v[118:121], v[130:133], v[194:197], v[118:121]
	v_mfma_f32_16x16x32_bf16 v[110:113], v[130:133], v[202:205], v[110:113]
	v_mfma_f32_16x16x32_bf16 v[46:49], v[138:141], v[202:205], v[46:49]
	v_mfma_f32_16x16x32_bf16 v[42:45], v[138:141], v[210:213], v[42:45]
	v_mfma_f32_16x16x32_bf16 v[106:109], v[130:133], v[210:213], v[106:109]
	v_mfma_f32_16x16x32_bf16 v[126:129], v[134:137], v[190:193], v[126:129]
	v_mfma_f32_16x16x32_bf16 v[62:65], v[142:145], v[190:193], v[62:65]
	v_mfma_f32_16x16x32_bf16 v[58:61], v[142:145], v[198:201], v[58:61]
	v_mfma_f32_16x16x32_bf16 v[118:121], v[134:137], v[198:201], v[118:121]
	v_mfma_f32_16x16x32_bf16 v[110:113], v[134:137], v[206:209], v[110:113]
	v_mfma_f32_16x16x32_bf16 v[46:49], v[142:145], v[206:209], v[46:49]
	v_mfma_f32_16x16x32_bf16 v[42:45], v[142:145], v[214:217], v[42:45]
	v_mfma_f32_16x16x32_bf16 v[106:109], v[134:137], v[214:217], v[106:109]
	s_setprio 0
	s_setprio 1
	v_mfma_f32_16x16x32_bf16 v[122:125], v[158:161], v[186:189], v[122:125]
	v_mfma_f32_16x16x32_bf16 v[54:57], v[178:181], v[186:189], v[54:57]
	v_mfma_f32_16x16x32_bf16 v[50:53], v[178:181], v[194:197], v[50:53]
	v_mfma_f32_16x16x32_bf16 v[114:117], v[158:161], v[194:197], v[114:117]
	v_mfma_f32_16x16x32_bf16 v[102:105], v[158:161], v[202:205], v[102:105]
	v_mfma_f32_16x16x32_bf16 v[38:41], v[178:181], v[202:205], v[38:41]
	v_mfma_f32_16x16x32_bf16 v[34:37], v[178:181], v[210:213], v[34:37]
	v_mfma_f32_16x16x32_bf16 v[98:101], v[158:161], v[210:213], v[98:101]
	v_mfma_f32_16x16x32_bf16 v[122:125], v[174:177], v[190:193], v[122:125]
	v_mfma_f32_16x16x32_bf16 v[54:57], v[182:185], v[190:193], v[54:57]
	v_mfma_f32_16x16x32_bf16 v[50:53], v[182:185], v[198:201], v[50:53]
	v_mfma_f32_16x16x32_bf16 v[114:117], v[174:177], v[198:201], v[114:117]
	v_mfma_f32_16x16x32_bf16 v[102:105], v[174:177], v[206:209], v[102:105]
	v_mfma_f32_16x16x32_bf16 v[38:41], v[182:185], v[206:209], v[38:41]
	v_mfma_f32_16x16x32_bf16 v[34:37], v[182:185], v[214:217], v[34:37]
	v_mfma_f32_16x16x32_bf16 v[98:101], v[174:177], v[214:217], v[98:101]
	s_setprio 0
	s_barrier
	s_add_i32 s61, s61, s84
	v_lshl_add_u64 v[218:219], s[36:37], 0, v[0:1]
	s_mov_b32 m0, s61
	ds_read_b128 v[186:189], v251 offset:16384
	ds_read_b128 v[190:193], v251 offset:17408
	ds_read_b128 v[194:197], v251 offset:18432
	ds_read_b128 v[198:201], v251 offset:19456
	ds_read_b128 v[202:205], v251 offset:20480
	ds_read_b128 v[206:209], v251 offset:21504
	ds_read_b128 v[210:213], v251 offset:22528
	ds_read_b128 v[214:217], v251 offset:23552
	global_load_lds_dwordx4 v[218:219], off
	s_add_i32 m0, s61, 0x2000
	s_add_u32 s94, s36, 0x20000
	v_lshl_add_u64 v[220:221], s[36:37], 0, v[150:151]
	s_addc_u32 s95, s37, 0
	s_add_i32 s61, s64, s84
	global_load_lds_dwordx4 v[220:221], off
	v_lshl_add_u64 v[222:223], s[94:95], 0, v[0:1]
	s_mov_b32 m0, s61
	v_lshl_add_u64 v[224:225], vcc, 0, v[148:149]
	global_load_lds_dwordx4 v[222:223], off
	v_lshl_add_u64 v[222:223], s[94:95], 0, v[150:151]
	s_add_i32 m0, s61, 0x2000
	s_nop 0
	global_load_lds_dwordx4 v[222:223], off
	v_lshl_add_u64 v[222:223], vcc, 0, v[146:147]
	s_mov_b32 m0, s85
	s_nop 0
	global_load_lds_dwordx4 v[222:223], off
	s_mov_b32 m0, s86
	s_nop 0
	global_load_lds_dwordx4 v[224:225], off
	s_waitcnt vmcnt(8)
	s_waitcnt lgkmcnt(0)
	s_barrier
; #define PG8_STAGE(bufoff, gbase, voff) do { _Pragma("unroll") for (int _i = 0; _i < 2; ++_i) \
;         __builtin_amdgcn_global_load_lds((const __attribute__((address_space(1))) unsigned*)((const char*)(gbase) + (voff)[_i]), (LAS unsigned*)(lds + (bufoff) + ldsw + _i * 8192), 16, 0, 0); } while (0)
; #define PG8_LDA(dst, b, h) do { _Pragma("unroll") for (int m = 0; m < 4; ++m) _Pragma("unroll") for (int k = 0; k < 2; ++k) dst[m][k] = *(const LAS bf16x8*)(lds + PG8_SA(b, h) + aoff + m * 2048 + k * 1024); } while (0)
; #define PG8_LDB(dst, b, h) do { _Pragma("unroll") for (int n = 0; n < 2; ++n) _Pragma("unroll") for (int k = 0; k < 2; ++k) dst[n][k] = *(const LAS bf16x8*)(lds + PG8_SB(b, h) + boff + n * 2048 + k * 1024); } while (0)
; #define PG8_MMA(ai, bj, At, Bt) do { __builtin_amdgcn_s_setprio(1); _Pragma("unroll") for (int m = 0; m < 4; ++m) _Pragma("unroll") for (int n = 0; n < 2; ++n) _Pragma("unroll") for (int k = 0; k < 2; ++k) \
;         acc[ai][bj][m][n] = __builtin_amdgcn_mfma_f32_16x16x32_bf16(Bt[n][k], At[m][k], acc[ai][bj][m][n], 0, 0, 0); __builtin_amdgcn_s_setprio(0); } while (0)
; #define PG8_WAIT_V(n) asm volatile("s_waitcnt vmcnt(" #n ")" ::: "memory")
; #define PG8_WAIT_L(n) asm volatile("s_waitcnt lgkmcnt(" #n ")" ::: "memory")
; #define PG8_BAR __builtin_amdgcn_s_barrier()
; #define PG8_SCHED __builtin_amdgcn_sched_barrier(0)
; template <class Epi, class SchedT, bool ALIGN_EPI, bool SP2>
; __device__ __forceinline__ void gemm_phase(LAS unsigned char* lds, const int ldk, const int nt, const SchedT& S, const Epi& E) {
;     ...
;             PG8_WAIT_V(8); PG8_WAIT_L(0); PG8_BAR; PG8_MMA(1, 0, At, B0); PG8_MMA(1, 1, At, B1); PG8_BAR; PG8_SCHED;
;             PG8_LDB(B0, 1, 0); PG8_LDB(B1, 1, 1); PG8_SCHED; PG8_LDA(At, 1, 0); PG8_STAGE(PG8_SA(0, 1), a2 + hstep, voffA);
;             PG8_WAIT_V(8); PG8_WAIT_L(0); PG8_BAR; PG8_MMA(0, 0, At, B0); PG8_MMA(0, 1, At, B1); PG8_BAR; PG8_SCHED;
	s_setprio 1
	s_waitcnt lgkmcnt(0)
	v_mfma_f32_16x16x32_bf16 v[94:97], v[130:133], v[186:189], v[94:97]
	v_mfma_f32_16x16x32_bf16 v[30:33], v[138:141], v[186:189], v[30:33]
	v_mfma_f32_16x16x32_bf16 v[26:29], v[138:141], v[194:197], v[26:29]
	v_mfma_f32_16x16x32_bf16 v[90:93], v[130:133], v[194:197], v[90:93]
	v_mfma_f32_16x16x32_bf16 v[78:81], v[130:133], v[202:205], v[78:81]
	v_mfma_f32_16x16x32_bf16 v[14:17], v[138:141], v[202:205], v[14:17]
	v_mfma_f32_16x16x32_bf16 v[10:13], v[138:141], v[210:213], v[10:13]
	v_mfma_f32_16x16x32_bf16 v[74:77], v[130:133], v[210:213], v[74:77]
	v_mfma_f32_16x16x32_bf16 v[94:97], v[134:137], v[190:193], v[94:97]
	v_mfma_f32_16x16x32_bf16 v[30:33], v[142:145], v[190:193], v[30:33]
	v_mfma_f32_16x16x32_bf16 v[26:29], v[142:145], v[198:201], v[26:29]
	v_mfma_f32_16x16x32_bf16 v[90:93], v[134:137], v[198:201], v[90:93]
	v_mfma_f32_16x16x32_bf16 v[78:81], v[134:137], v[206:209], v[78:81]
	v_mfma_f32_16x16x32_bf16 v[14:17], v[142:145], v[206:209], v[14:17]
	v_mfma_f32_16x16x32_bf16 v[10:13], v[142:145], v[214:217], v[10:13]
	v_mfma_f32_16x16x32_bf16 v[74:77], v[134:137], v[214:217], v[74:77]
	s_setprio 0
	s_setprio 1
	v_mfma_f32_16x16x32_bf16 v[86:89], v[158:161], v[186:189], v[86:89]
	v_mfma_f32_16x16x32_bf16 v[22:25], v[178:181], v[186:189], v[22:25]
	v_mfma_f32_16x16x32_bf16 v[18:21], v[178:181], v[194:197], v[18:21]
	v_mfma_f32_16x16x32_bf16 v[82:85], v[158:161], v[194:197], v[82:85]
	v_mfma_f32_16x16x32_bf16 v[70:73], v[158:161], v[202:205], v[70:73]
	v_mfma_f32_16x16x32_bf16 v[6:9], v[178:181], v[202:205], v[6:9]
	v_mfma_f32_16x16x32_bf16 v[2:5], v[178:181], v[210:213], v[2:5]
	v_mfma_f32_16x16x32_bf16 v[66:69], v[158:161], v[210:213], v[66:69]
	v_mfma_f32_16x16x32_bf16 v[86:89], v[174:177], v[190:193], v[86:89]
	v_mfma_f32_16x16x32_bf16 v[22:25], v[182:185], v[190:193], v[22:25]
	v_mfma_f32_16x16x32_bf16 v[18:21], v[182:185], v[198:201], v[18:21]
	v_mfma_f32_16x16x32_bf16 v[82:85], v[174:177], v[198:201], v[82:85]
	v_mfma_f32_16x16x32_bf16 v[70:73], v[174:177], v[206:209], v[70:73]
	v_mfma_f32_16x16x32_bf16 v[6:9], v[182:185], v[206:209], v[6:9]
	v_mfma_f32_16x16x32_bf16 v[2:5], v[182:185], v[214:217], v[2:5]
	v_mfma_f32_16x16x32_bf16 v[66:69], v[174:177], v[214:217], v[66:69]
	s_setprio 0
	s_barrier
	s_add_i32 s61, 0, 0x18000
	s_add_i32 s64, 0, 0x1c000
	v_add_u32_e32 v142, s61, v248
	v_add_u32_e32 v182, s64, v248
	ds_read_b128 v[130:133], v142
	ds_read_b128 v[134:137], v142 offset:1024
	ds_read_b128 v[138:141], v142 offset:2048
	ds_read_b128 v[142:145], v142 offset:3072
	ds_read_b128 v[158:161], v182
	ds_read_b128 v[174:177], v182 offset:1024
	ds_read_b128 v[178:181], v182 offset:2048
	ds_read_b128 v[182:185], v182 offset:3072
	s_add_u32 s94, vcc_lo, 0x80000
	s_addc_u32 s95, vcc_hi, 0
	s_mov_b32 m0, s87
	v_lshl_add_u64 v[226:227], s[94:95], 0, v[146:147]
	ds_read_b128 v[186:189], v251 offset:32768
	ds_read_b128 v[190:193], v251 offset:33792
	ds_read_b128 v[194:197], v251 offset:34816
	ds_read_b128 v[198:201], v251 offset:35840
	ds_read_b128 v[202:205], v251 offset:36864
	ds_read_b128 v[206:209], v251 offset:37888
	ds_read_b128 v[210:213], v251 offset:38912
	ds_read_b128 v[214:217], v251 offset:39936
	global_load_lds_dwordx4 v[226:227], off
	v_lshl_add_u64 v[226:227], s[94:95], 0, v[148:149]
	s_mov_b32 m0, s88
	s_nop 0
	global_load_lds_dwordx4 v[226:227], off
	s_waitcnt vmcnt(8)
	s_waitcnt lgkmcnt(0)
	s_barrier
	s_setprio 1
	s_waitcnt lgkmcnt(0)
	v_mfma_f32_16x16x32_bf16 v[126:129], v[130:133], v[186:189], v[126:129]
	v_mfma_f32_16x16x32_bf16 v[62:65], v[138:141], v[186:189], v[62:65]
	v_mfma_f32_16x16x32_bf16 v[58:61], v[138:141], v[194:197], v[58:61]
	v_mfma_f32_16x16x32_bf16 v[118:121], v[130:133], v[194:197], v[118:121]
	v_mfma_f32_16x16x32_bf16 v[110:113], v[130:133], v[202:205], v[110:113]
	v_mfma_f32_16x16x32_bf16 v[46:49], v[138:141], v[202:205], v[46:49]
	v_mfma_f32_16x16x32_bf16 v[42:45], v[138:141], v[210:213], v[42:45]
	v_mfma_f32_16x16x32_bf16 v[106:109], v[130:133], v[210:213], v[106:109]
	v_mfma_f32_16x16x32_bf16 v[126:129], v[134:137], v[190:193], v[126:129]
	v_mfma_f32_16x16x32_bf16 v[62:65], v[142:145], v[190:193], v[62:65]
	v_mfma_f32_16x16x32_bf16 v[58:61], v[142:145], v[198:201], v[58:61]
	v_mfma_f32_16x16x32_bf16 v[118:121], v[134:137], v[198:201], v[118:121]
	v_mfma_f32_16x16x32_bf16 v[110:113], v[134:137], v[206:209], v[110:113]
	v_mfma_f32_16x16x32_bf16 v[46:49], v[142:145], v[206:209], v[46:49]
	v_mfma_f32_16x16x32_bf16 v[42:45], v[142:145], v[214:217], v[42:45]
	v_mfma_f32_16x16x32_bf16 v[106:109], v[134:137], v[214:217], v[106:109]
	s_setprio 0
	s_setprio 1
	v_mfma_f32_16x16x32_bf16 v[122:125], v[158:161], v[186:189], v[122:125]
	v_mfma_f32_16x16x32_bf16 v[54:57], v[178:181], v[186:189], v[54:57]
	v_mfma_f32_16x16x32_bf16 v[50:53], v[178:181], v[194:197], v[50:53]
	v_mfma_f32_16x16x32_bf16 v[114:117], v[158:161], v[194:197], v[114:117]
	v_mfma_f32_16x16x32_bf16 v[102:105], v[158:161], v[202:205], v[102:105]
	v_mfma_f32_16x16x32_bf16 v[38:41], v[178:181], v[202:205], v[38:41]
	v_mfma_f32_16x16x32_bf16 v[34:37], v[178:181], v[210:213], v[34:37]
	v_mfma_f32_16x16x32_bf16 v[98:101], v[158:161], v[210:213], v[98:101]
	v_mfma_f32_16x16x32_bf16 v[122:125], v[174:177], v[190:193], v[122:125]
	v_mfma_f32_16x16x32_bf16 v[54:57], v[182:185], v[190:193], v[54:57]
	v_mfma_f32_16x16x32_bf16 v[50:53], v[182:185], v[198:201], v[50:53]
	v_mfma_f32_16x16x32_bf16 v[114:117], v[174:177], v[198:201], v[114:117]
	v_mfma_f32_16x16x32_bf16 v[102:105], v[174:177], v[206:209], v[102:105]
	v_mfma_f32_16x16x32_bf16 v[38:41], v[182:185], v[206:209], v[38:41]
	v_mfma_f32_16x16x32_bf16 v[34:37], v[182:185], v[214:217], v[34:37]
	v_mfma_f32_16x16x32_bf16 v[98:101], v[174:177], v[214:217], v[98:101]
	s_setprio 0
	s_barrier
; #define PG8_STAGE(bufoff, gbase, voff) do { _Pragma("unroll") for (int _i = 0; _i < 2; ++_i) \
;         __builtin_amdgcn_global_load_lds((const __attribute__((address_space(1))) unsigned*)((const char*)(gbase) + (voff)[_i]), (LAS unsigned*)(lds + (bufoff) + ldsw + _i * 8192), 16, 0, 0); } while (0)
; #define PG8_LDA(dst, b, h) do { _Pragma("unroll") for (int m = 0; m < 4; ++m) _Pragma("unroll") for (int k = 0; k < 2; ++k) dst[m][k] = *(const LAS bf16x8*)(lds + PG8_SA(b, h) + aoff + m * 2048 + k * 1024); } while (0)
; #define PG8_MMA(ai, bj, At, Bt) do { __builtin_amdgcn_s_setprio(1); _Pragma("unroll") for (int m = 0; m < 4; ++m) _Pragma("unroll") for (int n = 0; n < 2; ++n) _Pragma("unroll") for (int k = 0; k < 2; ++k) \
;         acc[ai][bj][m][n] = __builtin_amdgcn_mfma_f32_16x16x32_bf16(Bt[n][k], At[m][k], acc[ai][bj][m][n], 0, 0, 0); __builtin_amdgcn_s_setprio(0); } while (0)
; #define PG8_WAIT_V(n) asm volatile("s_waitcnt vmcnt(" #n ")" ::: "memory")
; #define PG8_WAIT_L(n) asm volatile("s_waitcnt lgkmcnt(" #n ")" ::: "memory")
; #define PG8_BAR __builtin_amdgcn_s_barrier()
; #define PG8_SCHED __builtin_amdgcn_sched_barrier(0)
; __device__ __forceinline__ float row_rstd(const float* ssp, int row, int fq) {
;     const f32x4 a = *(const f32x4*)(ssp + (size_t)row * 32 + 8 * fq), b = *(const f32x4*)(ssp + (size_t)row * 32 + 8 * fq + 4);
; template <class Epi, class SchedT, bool ALIGN_EPI, bool SP2>
; __device__ __forceinline__ void gemm_phase(LAS unsigned char* lds, const int ldk, const int nt, const SchedT& S, const Epi& E) {
;     ...
;             PG8_LDA(At, 1, 1); PG8_STAGE(PG8_SB(1, 0), b3, voffB); PG8_STAGE(PG8_SB(1, 1), b3 + hstepB, voffB); PG8_STAGE(PG8_SA(1, 0), a3, voffA);
;             PG8_WAIT_V(8); PG8_WAIT_L(0); PG8_BAR; PG8_MMA(1, 0, At, B0); PG8_MMA(1, 1, At, B1); PG8_BAR; PG8_SCHED;
	s_add_i32 s61, s61, s84
	v_lshl_add_u64 v[218:219], v[218:219], 0, s[24:25]
	s_mov_b32 m0, s61
	ds_read_b128 v[186:189], v251 offset:49152
	ds_read_b128 v[190:193], v251 offset:50176
	ds_read_b128 v[194:197], v251 offset:51200
	ds_read_b128 v[198:201], v251 offset:52224
	ds_read_b128 v[202:205], v251 offset:53248
	ds_read_b128 v[206:209], v251 offset:54272
	ds_read_b128 v[210:213], v251 offset:55296
	ds_read_b128 v[214:217], v251 offset:56320
	global_load_lds_dwordx4 v[218:219], off
	s_add_i32 m0, s61, 0x2000
	s_add_u32 s36, s36, 0x20080
	v_lshl_add_u64 v[218:219], v[220:221], 0, s[24:25]
	s_addc_u32 s37, s37, 0
	s_add_i32 s61, s64, s84
	global_load_lds_dwordx4 v[218:219], off
	v_lshl_add_u64 v[218:219], s[36:37], 0, v[0:1]
	s_mov_b32 m0, s61
	s_nop 0
	global_load_lds_dwordx4 v[218:219], off
	v_lshl_add_u64 v[218:219], s[36:37], 0, v[150:151]
	s_add_i32 m0, s61, 0x2000
	s_nop 0
	global_load_lds_dwordx4 v[218:219], off
	v_lshl_add_u64 v[218:219], v[222:223], 0, s[24:25]
	s_mov_b32 m0, s89
	s_nop 0
	global_load_lds_dwordx4 v[218:219], off
	v_lshl_add_u64 v[218:219], v[224:225], 0, s[24:25]
	s_mov_b32 m0, s90
	s_nop 0
	global_load_lds_dwordx4 v[218:219], off
	s_waitcnt vmcnt(8)
	s_waitcnt lgkmcnt(0)
	s_barrier
	s_setprio 1
	s_waitcnt lgkmcnt(0)
	v_mfma_f32_16x16x32_bf16 v[94:97], v[130:133], v[186:189], v[94:97]
	v_mfma_f32_16x16x32_bf16 v[30:33], v[138:141], v[186:189], v[30:33]
	v_mfma_f32_16x16x32_bf16 v[26:29], v[138:141], v[194:197], v[26:29]
	v_mfma_f32_16x16x32_bf16 v[90:93], v[130:133], v[194:197], v[90:93]
	v_mfma_f32_16x16x32_bf16 v[78:81], v[130:133], v[202:205], v[78:81]
	v_mfma_f32_16x16x32_bf16 v[14:17], v[138:141], v[202:205], v[14:17]
	v_mfma_f32_16x16x32_bf16 v[10:13], v[138:141], v[210:213], v[10:13]
	v_mfma_f32_16x16x32_bf16 v[74:77], v[130:133], v[210:213], v[74:77]
	v_mfma_f32_16x16x32_bf16 v[94:97], v[134:137], v[190:193], v[94:97]
	v_mfma_f32_16x16x32_bf16 v[30:33], v[142:145], v[190:193], v[30:33]
	v_mfma_f32_16x16x32_bf16 v[26:29], v[142:145], v[198:201], v[26:29]
	v_mfma_f32_16x16x32_bf16 v[90:93], v[134:137], v[198:201], v[90:93]
	v_mfma_f32_16x16x32_bf16 v[78:81], v[134:137], v[206:209], v[78:81]
	v_mfma_f32_16x16x32_bf16 v[14:17], v[142:145], v[206:209], v[14:17]
	v_mfma_f32_16x16x32_bf16 v[10:13], v[142:145], v[214:217], v[10:13]
	v_mfma_f32_16x16x32_bf16 v[74:77], v[134:137], v[214:217], v[74:77]
	s_setprio 0
	s_setprio 1
	v_mfma_f32_16x16x32_bf16 v[86:89], v[158:161], v[186:189], v[86:89]
	v_mfma_f32_16x16x32_bf16 v[22:25], v[178:181], v[186:189], v[22:25]
	v_mfma_f32_16x16x32_bf16 v[18:21], v[178:181], v[194:197], v[18:21]
	v_mfma_f32_16x16x32_bf16 v[82:85], v[158:161], v[194:197], v[82:85]
	v_mfma_f32_16x16x32_bf16 v[70:73], v[158:161], v[202:205], v[70:73]
	v_mfma_f32_16x16x32_bf16 v[6:9], v[178:181], v[202:205], v[6:9]
	v_mfma_f32_16x16x32_bf16 v[2:5], v[178:181], v[210:213], v[2:5]
	v_mfma_f32_16x16x32_bf16 v[66:69], v[158:161], v[210:213], v[66:69]
	v_mfma_f32_16x16x32_bf16 v[86:89], v[174:177], v[190:193], v[86:89]
	v_mfma_f32_16x16x32_bf16 v[22:25], v[182:185], v[190:193], v[22:25]
	v_mfma_f32_16x16x32_bf16 v[18:21], v[182:185], v[198:201], v[18:21]
	v_mfma_f32_16x16x32_bf16 v[82:85], v[174:177], v[198:201], v[82:85]
	v_mfma_f32_16x16x32_bf16 v[70:73], v[174:177], v[206:209], v[70:73]
	v_mfma_f32_16x16x32_bf16 v[6:9], v[182:185], v[206:209], v[6:9]
	v_mfma_f32_16x16x32_bf16 v[2:5], v[182:185], v[214:217], v[2:5]
	v_mfma_f32_16x16x32_bf16 v[66:69], v[174:177], v[214:217], v[66:69]
	s_setprio 0
	s_barrier
	s_add_i32 s59, s59, 2
	s_add_u32 s34, s34, 0x100
	s_addc_u32 s35, s35, 0
	s_add_u32 s13, s13, 0x100
	s_addc_u32 s17, s17, 0
	s_cmp_gt_u32 s59, 29
	s_cbranch_scc0 .LBB0_752
	v_lshl_add_u32 v130, s12, 8, v247
	v_lshlrev_b32_e32 v140, 7, v130
	v_mov_b32_e32 v141, 0
	v_lshl_add_u64 v[132:133], v[152:153], 0, v[140:141]
	v_add_u32_e32 v140, 0x1000, v140
	v_lshl_add_u64 v[134:135], v[152:153], 0, v[140:141]
	v_add_u32_e32 v140, 0x3000, v140
	v_lshl_add_u64 v[136:137], v[152:153], 0, v[140:141]
	v_add_u32_e32 v140, 0x1000, v140
	v_lshl_add_u64 v[138:139], v[152:153], 0, v[140:141]
	global_load_dwordx4 v[174:177], v[132:133], off
	global_load_dwordx4 v[178:181], v[132:133], off offset:16
	global_load_dwordx4 v[182:185], v[132:133], off offset:2048
	global_load_dwordx4 v[186:189], v[132:133], off offset:2064
	global_load_dwordx4 v[190:193], v[134:135], off
	global_load_dwordx4 v[194:197], v[134:135], off offset:16
	global_load_dwordx4 v[198:201], v[134:135], off offset:2048
	global_load_dwordx4 v[202:205], v[134:135], off offset:2064
	global_load_dwordx4 v[206:209], v[136:137], off
	global_load_dwordx4 v[210:213], v[136:137], off offset:16
	global_load_dwordx4 v[214:217], v[136:137], off offset:2048
	global_load_dwordx4 v[218:221], v[136:137], off offset:2064
	global_load_dwordx4 v[222:225], v[138:139], off
	global_load_dwordx4 v[226:229], v[138:139], off offset:16
	global_load_dwordx4 v[230:233], v[138:139], off offset:2048
	global_load_dwordx4 v[234:237], v[138:139], off offset:2064
	v_xor_b32_e32 v238, 16, v241
	v_xor_b32_e32 v239, 32, v241
	v_lshlrev_b32_e32 v238, 2, v238
	v_lshlrev_b32_e32 v239, 2, v239
	s_and_b64 vcc, exec, s[56:57]
	s_cbranch_vccz .LBB0_755
	s_barrier

; #define PG8_STAGE(bufoff, gbase, voff) do { _Pragma("unroll") for (int _i = 0; _i < 2; ++_i) \
;         __builtin_amdgcn_global_load_lds((const __attribute__((address_space(1))) unsigned*)((const char*)(gbase) + (voff)[_i]), (LAS unsigned*)(lds + (bufoff) + ldsw + _i * 8192), 16, 0, 0); } while (0)
; #define PG8_LDA(dst, b, h) do { _Pragma("unroll") for (int m = 0; m < 4; ++m) _Pragma("unroll") for (int k = 0; k < 2; ++k) dst[m][k] = *(const LAS bf16x8*)(lds + PG8_SA(b, h) + aoff + m * 2048 + k * 1024); } while (0)
; #define PG8_LDB(dst, b, h) do { _Pragma("unroll") for (int n = 0; n < 2; ++n) _Pragma("unroll") for (int k = 0; k < 2; ++k) dst[n][k] = *(const LAS bf16x8*)(lds + PG8_SB(b, h) + boff + n * 2048 + k * 1024); } while (0)
; #define PG8_MMA(ai, bj, At, Bt) do { __builtin_amdgcn_s_setprio(1); _Pragma("unroll") for (int m = 0; m < 4; ++m) _Pragma("unroll") for (int n = 0; n < 2; ++n) _Pragma("unroll") for (int k = 0; k < 2; ++k) \
;         acc[ai][bj][m][n] = __builtin_amdgcn_mfma_f32_16x16x32_bf16(Bt[n][k], At[m][k], acc[ai][bj][m][n], 0, 0, 0); __builtin_amdgcn_s_setprio(0); } while (0)
; #define PG8_WAIT_V(n) asm volatile("s_waitcnt vmcnt(" #n ")" ::: "memory")
; #define PG8_WAIT_L(n) asm volatile("s_waitcnt lgkmcnt(" #n ")" ::: "memory")
; #define PG8_BAR __builtin_amdgcn_s_barrier()
; #define PG8_SCHED __builtin_amdgcn_sched_barrier(0)
; template <class Epi, class SchedT, bool ALIGN_EPI, bool SP2>
; __device__ __forceinline__ void gemm_phase(LAS unsigned char* lds, const int ldk, const int nt, const SchedT& S, const Epi& E) {
;     ...
;             const bool last = (t == nt - 2);
;             const char* a1 = cA + (size_t)(t + 1) * kstep;
;             const char* a2 = last ? nA : cA + (size_t)(t + 2) * kstep; const char* b2 = last ? nB : cB + (size_t)(t + 2) * kstep;
;             const char* a3 = a2 + kstep; const char* b3 = b2 + kstep;
;             if constexpr (SP2) {
;             PG8_LDB(B0, 0, 0); PG8_LDB(B1, 0, 1); PG8_SCHED; PG8_LDA(At, 0, 0); PG8_STAGE(PG8_SA(1, 1), a1 + hstep, voffA);
;             PG8_WAIT_V(8); PG8_WAIT_L(0); PG8_BAR; PG8_MMA(0, 0, At, B0); PG8_MMA(0, 1, At, B1); PG8_BAR; PG8_SCHED;
;             PG8_LDA(At, 0, 1); PG8_STAGE(PG8_SB(0, 0), b2, voffB); PG8_STAGE(PG8_SB(0, 1), b2 + hstepB, voffB); PG8_STAGE(PG8_SA(0, 0), a2, voffA);
.LBB0_948:
	s_add_u32 s16, s12, 0x100
	s_addc_u32 s17, s13, 0
	s_add_i32 s64, 0, 0x10000
	s_cmpk_eq_i32 s83, 0x52
	s_cselect_b32 s47, s1, s17
	s_cselect_b32 s46, s0, s16
	v_add_u32_e32 v144, s64, v147
	s_cselect_b32 s45, s43, s82
	s_cselect_b32 s44, s42, s81
	s_add_i32 s65, 0, 0x14000
	ds_read_b128 v[140:143], v144
	ds_read_b128 v[150:153], v144 offset:1024
	ds_read_b128 v[154:157], v144 offset:2048
	ds_read_b128 v[158:161], v144 offset:3072
	v_add_u32_e32 v144, s65, v147
	ds_read_b128 v[174:177], v144
	ds_read_b128 v[178:181], v144 offset:1024
	ds_read_b128 v[182:185], v144 offset:2048
	ds_read_b128 v[186:189], v144 offset:3072
	v_lshl_add_u64 v[144:145], s[12:13], 0, v[136:137]
	s_add_i32 m0, s53, 0xc000
	ds_read_b128 v[190:193], v149
	ds_read_b128 v[194:197], v149 offset:1024
	ds_read_b128 v[198:201], v149 offset:2048
	ds_read_b128 v[202:205], v149 offset:3072
	ds_read_b128 v[206:209], v149 offset:4096
	ds_read_b128 v[210:213], v149 offset:5120
	ds_read_b128 v[214:217], v149 offset:6144
	ds_read_b128 v[218:221], v149 offset:7168
	global_load_lds_dwordx4 v[144:145], off
	v_lshl_add_u64 v[144:145], s[12:13], 0, v[138:139]
	s_add_i32 m0, s53, 0xe000
	s_nop 0
	global_load_lds_dwordx4 v[144:145], off
	s_waitcnt vmcnt(8)
	s_waitcnt lgkmcnt(0)
	s_barrier
	s_setprio 1
	s_waitcnt lgkmcnt(0)
	v_mfma_f32_16x16x32_bf16 v[126:129], v[140:143], v[190:193], v[126:129]
	v_mfma_f32_16x16x32_bf16 v[122:125], v[154:157], v[190:193], v[122:125]
	v_mfma_f32_16x16x32_bf16 v[106:109], v[154:157], v[198:201], v[106:109]
	v_mfma_f32_16x16x32_bf16 v[110:113], v[140:143], v[198:201], v[110:113]
	v_mfma_f32_16x16x32_bf16 v[94:97], v[140:143], v[206:209], v[94:97]
	v_mfma_f32_16x16x32_bf16 v[90:93], v[154:157], v[206:209], v[90:93]
	v_mfma_f32_16x16x32_bf16 v[74:77], v[154:157], v[214:217], v[74:77]
	v_mfma_f32_16x16x32_bf16 v[78:81], v[140:143], v[214:217], v[78:81]
	v_mfma_f32_16x16x32_bf16 v[126:129], v[150:153], v[194:197], v[126:129]
	v_mfma_f32_16x16x32_bf16 v[122:125], v[158:161], v[194:197], v[122:125]
	v_mfma_f32_16x16x32_bf16 v[106:109], v[158:161], v[202:205], v[106:109]
	v_mfma_f32_16x16x32_bf16 v[110:113], v[150:153], v[202:205], v[110:113]
	v_mfma_f32_16x16x32_bf16 v[94:97], v[150:153], v[210:213], v[94:97]
	v_mfma_f32_16x16x32_bf16 v[90:93], v[158:161], v[210:213], v[90:93]
	v_mfma_f32_16x16x32_bf16 v[74:77], v[158:161], v[218:221], v[74:77]
	v_mfma_f32_16x16x32_bf16 v[78:81], v[150:153], v[218:221], v[78:81]
	s_setprio 0
	s_setprio 1
	v_mfma_f32_16x16x32_bf16 v[118:121], v[174:177], v[190:193], v[118:121]
	v_mfma_f32_16x16x32_bf16 v[114:117], v[182:185], v[190:193], v[114:117]
	v_mfma_f32_16x16x32_bf16 v[98:101], v[182:185], v[198:201], v[98:101]
	v_mfma_f32_16x16x32_bf16 v[102:105], v[174:177], v[198:201], v[102:105]
	v_mfma_f32_16x16x32_bf16 v[86:89], v[174:177], v[206:209], v[86:89]
	v_mfma_f32_16x16x32_bf16 v[82:85], v[182:185], v[206:209], v[82:85]
	v_mfma_f32_16x16x32_bf16 v[66:69], v[182:185], v[214:217], v[66:69]
	v_mfma_f32_16x16x32_bf16 v[70:73], v[174:177], v[214:217], v[70:73]
	v_mfma_f32_16x16x32_bf16 v[118:121], v[178:181], v[194:197], v[118:121]
	v_mfma_f32_16x16x32_bf16 v[114:117], v[186:189], v[194:197], v[114:117]
	v_mfma_f32_16x16x32_bf16 v[98:101], v[186:189], v[202:205], v[98:101]
	v_mfma_f32_16x16x32_bf16 v[102:105], v[178:181], v[202:205], v[102:105]
	v_mfma_f32_16x16x32_bf16 v[86:89], v[178:181], v[210:213], v[86:89]
	v_mfma_f32_16x16x32_bf16 v[82:85], v[186:189], v[210:213], v[82:85]
	v_mfma_f32_16x16x32_bf16 v[66:69], v[186:189], v[218:221], v[66:69]
	v_mfma_f32_16x16x32_bf16 v[70:73], v[178:181], v[218:221], v[70:73]
	s_setprio 0
	s_barrier
	s_add_i32 s12, s64, s52
	v_lshl_add_u64 v[144:145], s[44:45], 0, v[0:1]
	s_mov_b32 m0, s12
	ds_read_b128 v[190:193], v149 offset:16384
	ds_read_b128 v[194:197], v149 offset:17408
	ds_read_b128 v[198:201], v149 offset:18432
	ds_read_b128 v[202:205], v149 offset:19456
	ds_read_b128 v[206:209], v149 offset:20480
	ds_read_b128 v[210:213], v149 offset:21504
	ds_read_b128 v[214:217], v149 offset:22528
	ds_read_b128 v[218:221], v149 offset:23552
	global_load_lds_dwordx4 v[144:145], off
	s_add_i32 m0, s12, 0x2000
	s_add_u32 s12, s44, 0x56000
	v_lshl_add_u64 v[222:223], s[44:45], 0, v[134:135]
	s_addc_u32 s13, s45, 0
	s_add_i32 s64, s65, s52
	global_load_lds_dwordx4 v[222:223], off
	v_lshl_add_u64 v[224:225], s[12:13], 0, v[0:1]
	s_mov_b32 m0, s64
	v_lshl_add_u64 v[226:227], s[46:47], 0, v[132:133]
	global_load_lds_dwordx4 v[224:225], off
	v_lshl_add_u64 v[224:225], s[12:13], 0, v[134:135]
	s_add_i32 m0, s64, 0x2000
	s_nop 0
	global_load_lds_dwordx4 v[224:225], off
	v_lshl_add_u64 v[224:225], s[46:47], 0, v[130:131]
	s_mov_b32 m0, s53
	s_nop 0
	global_load_lds_dwordx4 v[224:225], off
	s_mov_b32 m0, s54
	s_nop 0
	global_load_lds_dwordx4 v[226:227], off
	s_waitcnt vmcnt(8)
	s_waitcnt lgkmcnt(0)
	s_barrier
; #define PG8_STAGE(bufoff, gbase, voff) do { _Pragma("unroll") for (int _i = 0; _i < 2; ++_i) \
;         __builtin_amdgcn_global_load_lds((const __attribute__((address_space(1))) unsigned*)((const char*)(gbase) + (voff)[_i]), (LAS unsigned*)(lds + (bufoff) + ldsw + _i * 8192), 16, 0, 0); } while (0)
; #define PG8_LDA(dst, b, h) do { _Pragma("unroll") for (int m = 0; m < 4; ++m) _Pragma("unroll") for (int k = 0; k < 2; ++k) dst[m][k] = *(const LAS bf16x8*)(lds + PG8_SA(b, h) + aoff + m * 2048 + k * 1024); } while (0)
; #define PG8_LDB(dst, b, h) do { _Pragma("unroll") for (int n = 0; n < 2; ++n) _Pragma("unroll") for (int k = 0; k < 2; ++k) dst[n][k] = *(const LAS bf16x8*)(lds + PG8_SB(b, h) + boff + n * 2048 + k * 1024); } while (0)
; #define PG8_MMA(ai, bj, At, Bt) do { __builtin_amdgcn_s_setprio(1); _Pragma("unroll") for (int m = 0; m < 4; ++m) _Pragma("unroll") for (int n = 0; n < 2; ++n) _Pragma("unroll") for (int k = 0; k < 2; ++k) \
;         acc[ai][bj][m][n] = __builtin_amdgcn_mfma_f32_16x16x32_bf16(Bt[n][k], At[m][k], acc[ai][bj][m][n], 0, 0, 0); __builtin_amdgcn_s_setprio(0); } while (0)
; #define PG8_WAIT_V(n) asm volatile("s_waitcnt vmcnt(" #n ")" ::: "memory")
; #define PG8_WAIT_L(n) asm volatile("s_waitcnt lgkmcnt(" #n ")" ::: "memory")
; #define PG8_BAR __builtin_amdgcn_s_barrier()
; #define PG8_SCHED __builtin_amdgcn_sched_barrier(0)
; template <class Epi, class SchedT, bool ALIGN_EPI, bool SP2>
; __device__ __forceinline__ void gemm_phase(LAS unsigned char* lds, const int ldk, const int nt, const SchedT& S, const Epi& E) {
;     ...
;             PG8_WAIT_V(8); PG8_WAIT_L(0); PG8_BAR; PG8_MMA(1, 0, At, B0); PG8_MMA(1, 1, At, B1); PG8_BAR; PG8_SCHED;
;             PG8_LDB(B0, 1, 0); PG8_LDB(B1, 1, 1); PG8_SCHED; PG8_LDA(At, 1, 0); PG8_STAGE(PG8_SA(0, 1), a2 + hstep, voffA);
;             PG8_WAIT_V(8); PG8_WAIT_L(0); PG8_BAR; PG8_MMA(0, 0, At, B0); PG8_MMA(0, 1, At, B1); PG8_BAR; PG8_SCHED;
	s_setprio 1
	s_waitcnt lgkmcnt(0)
	v_mfma_f32_16x16x32_bf16 v[62:65], v[140:143], v[190:193], v[62:65]
	v_mfma_f32_16x16x32_bf16 v[58:61], v[154:157], v[190:193], v[58:61]
	v_mfma_f32_16x16x32_bf16 v[42:45], v[154:157], v[198:201], v[42:45]
	v_mfma_f32_16x16x32_bf16 v[46:49], v[140:143], v[198:201], v[46:49]
	v_mfma_f32_16x16x32_bf16 v[30:33], v[140:143], v[206:209], v[30:33]
	v_mfma_f32_16x16x32_bf16 v[26:29], v[154:157], v[206:209], v[26:29]
	v_mfma_f32_16x16x32_bf16 v[10:13], v[154:157], v[214:217], v[10:13]
	v_mfma_f32_16x16x32_bf16 v[14:17], v[140:143], v[214:217], v[14:17]
	v_mfma_f32_16x16x32_bf16 v[62:65], v[150:153], v[194:197], v[62:65]
	v_mfma_f32_16x16x32_bf16 v[58:61], v[158:161], v[194:197], v[58:61]
	v_mfma_f32_16x16x32_bf16 v[42:45], v[158:161], v[202:205], v[42:45]
	v_mfma_f32_16x16x32_bf16 v[46:49], v[150:153], v[202:205], v[46:49]
	v_mfma_f32_16x16x32_bf16 v[30:33], v[150:153], v[210:213], v[30:33]
	v_mfma_f32_16x16x32_bf16 v[26:29], v[158:161], v[210:213], v[26:29]
	v_mfma_f32_16x16x32_bf16 v[10:13], v[158:161], v[218:221], v[10:13]
	v_mfma_f32_16x16x32_bf16 v[14:17], v[150:153], v[218:221], v[14:17]
	s_setprio 0
	s_setprio 1
	v_mfma_f32_16x16x32_bf16 v[54:57], v[174:177], v[190:193], v[54:57]
	v_mfma_f32_16x16x32_bf16 v[50:53], v[182:185], v[190:193], v[50:53]
	v_mfma_f32_16x16x32_bf16 v[34:37], v[182:185], v[198:201], v[34:37]
	v_mfma_f32_16x16x32_bf16 v[38:41], v[174:177], v[198:201], v[38:41]
	v_mfma_f32_16x16x32_bf16 v[22:25], v[174:177], v[206:209], v[22:25]
	v_mfma_f32_16x16x32_bf16 v[18:21], v[182:185], v[206:209], v[18:21]
	v_mfma_f32_16x16x32_bf16 v[2:5], v[182:185], v[214:217], v[2:5]
	v_mfma_f32_16x16x32_bf16 v[6:9], v[174:177], v[214:217], v[6:9]
	v_mfma_f32_16x16x32_bf16 v[54:57], v[178:181], v[194:197], v[54:57]
	v_mfma_f32_16x16x32_bf16 v[50:53], v[186:189], v[194:197], v[50:53]
	v_mfma_f32_16x16x32_bf16 v[34:37], v[186:189], v[202:205], v[34:37]
	v_mfma_f32_16x16x32_bf16 v[38:41], v[178:181], v[202:205], v[38:41]
	v_mfma_f32_16x16x32_bf16 v[22:25], v[178:181], v[210:213], v[22:25]
	v_mfma_f32_16x16x32_bf16 v[18:21], v[186:189], v[210:213], v[18:21]
	v_mfma_f32_16x16x32_bf16 v[2:5], v[186:189], v[218:221], v[2:5]
	v_mfma_f32_16x16x32_bf16 v[6:9], v[178:181], v[218:221], v[6:9]
	s_setprio 0
	s_barrier
	s_add_i32 s64, 0, 0x18000
	s_add_i32 s65, 0, 0x1c000
	v_add_u32_e32 v158, s64, v147
	v_add_u32_e32 v186, s65, v147
	ds_read_b128 v[140:143], v158
	ds_read_b128 v[150:153], v158 offset:1024
	ds_read_b128 v[154:157], v158 offset:2048
	ds_read_b128 v[158:161], v158 offset:3072
	ds_read_b128 v[174:177], v186
	ds_read_b128 v[178:181], v186 offset:1024
	ds_read_b128 v[182:185], v186 offset:2048
	ds_read_b128 v[186:189], v186 offset:3072
	s_add_u32 s12, s46, 0x158000
	s_addc_u32 s13, s47, 0
	s_mov_b32 m0, s55
	v_lshl_add_u64 v[228:229], s[12:13], 0, v[130:131]
	ds_read_b128 v[190:193], v149 offset:32768
	ds_read_b128 v[194:197], v149 offset:33792
	ds_read_b128 v[198:201], v149 offset:34816
	ds_read_b128 v[202:205], v149 offset:35840
	ds_read_b128 v[206:209], v149 offset:36864
	ds_read_b128 v[210:213], v149 offset:37888
	ds_read_b128 v[214:217], v149 offset:38912
	ds_read_b128 v[218:221], v149 offset:39936
	global_load_lds_dwordx4 v[228:229], off
	v_lshl_add_u64 v[228:229], s[12:13], 0, v[132:133]
	s_mov_b32 m0, s56
	s_nop 0
	global_load_lds_dwordx4 v[228:229], off
	s_waitcnt vmcnt(8)
	s_waitcnt lgkmcnt(0)
	s_barrier
	s_setprio 1
	s_waitcnt lgkmcnt(0)
	v_mfma_f32_16x16x32_bf16 v[126:129], v[140:143], v[190:193], v[126:129]
	v_mfma_f32_16x16x32_bf16 v[122:125], v[154:157], v[190:193], v[122:125]
	v_mfma_f32_16x16x32_bf16 v[106:109], v[154:157], v[198:201], v[106:109]
	v_mfma_f32_16x16x32_bf16 v[110:113], v[140:143], v[198:201], v[110:113]
	v_mfma_f32_16x16x32_bf16 v[94:97], v[140:143], v[206:209], v[94:97]
	v_mfma_f32_16x16x32_bf16 v[90:93], v[154:157], v[206:209], v[90:93]
	v_mfma_f32_16x16x32_bf16 v[74:77], v[154:157], v[214:217], v[74:77]
	v_mfma_f32_16x16x32_bf16 v[78:81], v[140:143], v[214:217], v[78:81]
	v_mfma_f32_16x16x32_bf16 v[126:129], v[150:153], v[194:197], v[126:129]
	v_mfma_f32_16x16x32_bf16 v[122:125], v[158:161], v[194:197], v[122:125]
	v_mfma_f32_16x16x32_bf16 v[106:109], v[158:161], v[202:205], v[106:109]
	v_mfma_f32_16x16x32_bf16 v[110:113], v[150:153], v[202:205], v[110:113]
	v_mfma_f32_16x16x32_bf16 v[94:97], v[150:153], v[210:213], v[94:97]
	v_mfma_f32_16x16x32_bf16 v[90:93], v[158:161], v[210:213], v[90:93]
	v_mfma_f32_16x16x32_bf16 v[74:77], v[158:161], v[218:221], v[74:77]
	v_mfma_f32_16x16x32_bf16 v[78:81], v[150:153], v[218:221], v[78:81]
	s_setprio 0
	s_setprio 1
	v_mfma_f32_16x16x32_bf16 v[118:121], v[174:177], v[190:193], v[118:121]
	v_mfma_f32_16x16x32_bf16 v[114:117], v[182:185], v[190:193], v[114:117]
	v_mfma_f32_16x16x32_bf16 v[98:101], v[182:185], v[198:201], v[98:101]
	v_mfma_f32_16x16x32_bf16 v[102:105], v[174:177], v[198:201], v[102:105]
	v_mfma_f32_16x16x32_bf16 v[86:89], v[174:177], v[206:209], v[86:89]
	v_mfma_f32_16x16x32_bf16 v[82:85], v[182:185], v[206:209], v[82:85]
	v_mfma_f32_16x16x32_bf16 v[66:69], v[182:185], v[214:217], v[66:69]
	v_mfma_f32_16x16x32_bf16 v[70:73], v[174:177], v[214:217], v[70:73]
	v_mfma_f32_16x16x32_bf16 v[118:121], v[178:181], v[194:197], v[118:121]
	v_mfma_f32_16x16x32_bf16 v[114:117], v[186:189], v[194:197], v[114:117]
	v_mfma_f32_16x16x32_bf16 v[98:101], v[186:189], v[202:205], v[98:101]
	v_mfma_f32_16x16x32_bf16 v[102:105], v[178:181], v[202:205], v[102:105]
	v_mfma_f32_16x16x32_bf16 v[86:89], v[178:181], v[210:213], v[86:89]
	v_mfma_f32_16x16x32_bf16 v[82:85], v[186:189], v[210:213], v[82:85]
	v_mfma_f32_16x16x32_bf16 v[66:69], v[186:189], v[218:221], v[66:69]
	v_mfma_f32_16x16x32_bf16 v[70:73], v[178:181], v[218:221], v[70:73]
	s_setprio 0
	s_barrier
; #define PG8_STAGE(bufoff, gbase, voff) do { _Pragma("unroll") for (int _i = 0; _i < 2; ++_i) \
;         __builtin_amdgcn_global_load_lds((const __attribute__((address_space(1))) unsigned*)((const char*)(gbase) + (voff)[_i]), (LAS unsigned*)(lds + (bufoff) + ldsw + _i * 8192), 16, 0, 0); } while (0)
; #define PG8_LDA(dst, b, h) do { _Pragma("unroll") for (int m = 0; m < 4; ++m) _Pragma("unroll") for (int k = 0; k < 2; ++k) dst[m][k] = *(const LAS bf16x8*)(lds + PG8_SA(b, h) + aoff + m * 2048 + k * 1024); } while (0)
; #define PG8_MMA(ai, bj, At, Bt) do { __builtin_amdgcn_s_setprio(1); _Pragma("unroll") for (int m = 0; m < 4; ++m) _Pragma("unroll") for (int n = 0; n < 2; ++n) _Pragma("unroll") for (int k = 0; k < 2; ++k) \
;         acc[ai][bj][m][n] = __builtin_amdgcn_mfma_f32_16x16x32_bf16(Bt[n][k], At[m][k], acc[ai][bj][m][n], 0, 0, 0); __builtin_amdgcn_s_setprio(0); } while (0)
; #define PG8_WAIT_V(n) asm volatile("s_waitcnt vmcnt(" #n ")" ::: "memory")
; #define PG8_WAIT_L(n) asm volatile("s_waitcnt lgkmcnt(" #n ")" ::: "memory")
; #define PG8_BAR __builtin_amdgcn_s_barrier()
; #define PG8_SCHED __builtin_amdgcn_sched_barrier(0)
; template <class Epi, class SchedT, bool ALIGN_EPI, bool SP2>
; __device__ __forceinline__ void gemm_phase(LAS unsigned char* lds, const int ldk, const int nt, const SchedT& S, const Epi& E) {
;     ...
;             PG8_LDA(At, 1, 1); PG8_STAGE(PG8_SB(1, 0), b3, voffB); PG8_STAGE(PG8_SB(1, 1), b3 + hstepB, voffB); PG8_STAGE(PG8_SA(1, 0), a3, voffA);
;             PG8_WAIT_V(8); PG8_WAIT_L(0); PG8_BAR; PG8_MMA(1, 0, At, B0); PG8_MMA(1, 1, At, B1); PG8_BAR; PG8_SCHED;
;     __device__ __forceinline__ void operator()(f32x4 (&acc)[2][2][4][2], const Unit& u, int wr, int wc, int fr, int fq) const {
;         const int row0 = u.pm * BM + wr * 64 + fr, col0 = u.pn * BM + wc * 64 + 8 * fq;
; #pragma unroll
;         for (int ai = 0; ai < 2; ++ai)
; #pragma unroll
;             for (int m = 0; m < 4; ++m) {
;                 const int row = row0 + ai * HALF + m * 16; float sq = 0.f;
; #pragma unroll
;                 for (int bj = 0; bj < 2; ++bj) {
;                     const size_t off = (size_t)row * D + col0 + bj * 32;
;                     const u32x4 xw = *(const u32x4*)(xin + off);
	s_add_i32 s12, s64, s52
	v_lshl_add_u64 v[144:145], v[144:145], 0, s[24:25]
	s_mov_b32 m0, s12
	ds_read_b128 v[190:193], v149 offset:49152
	ds_read_b128 v[194:197], v149 offset:50176
	ds_read_b128 v[198:201], v149 offset:51200
	ds_read_b128 v[202:205], v149 offset:52224
	ds_read_b128 v[206:209], v149 offset:53248
	ds_read_b128 v[210:213], v149 offset:54272
	ds_read_b128 v[214:217], v149 offset:55296
	ds_read_b128 v[218:221], v149 offset:56320
	global_load_lds_dwordx4 v[144:145], off
	s_add_i32 m0, s12, 0x2000
	s_add_u32 s12, s44, 0x56080
	v_lshl_add_u64 v[144:145], v[222:223], 0, s[24:25]
	s_addc_u32 s13, s45, 0
	s_add_i32 s44, s65, s52
	global_load_lds_dwordx4 v[144:145], off
	v_lshl_add_u64 v[144:145], s[12:13], 0, v[0:1]
	s_mov_b32 m0, s44
	s_nop 0
	global_load_lds_dwordx4 v[144:145], off
	v_lshl_add_u64 v[144:145], s[12:13], 0, v[134:135]
	s_add_i32 m0, s44, 0x2000
	s_nop 0
	global_load_lds_dwordx4 v[144:145], off
	v_lshl_add_u64 v[144:145], v[224:225], 0, s[24:25]
	s_mov_b32 m0, s58
	s_nop 0
	global_load_lds_dwordx4 v[144:145], off
	v_lshl_add_u64 v[144:145], v[226:227], 0, s[24:25]
	s_mov_b32 m0, s59
	s_nop 0
	global_load_lds_dwordx4 v[144:145], off
	s_waitcnt vmcnt(8)
	s_waitcnt lgkmcnt(0)
	s_barrier
	s_setprio 1
	s_waitcnt lgkmcnt(0)
	v_mfma_f32_16x16x32_bf16 v[62:65], v[140:143], v[190:193], v[62:65]
	v_mfma_f32_16x16x32_bf16 v[58:61], v[154:157], v[190:193], v[58:61]
	v_mfma_f32_16x16x32_bf16 v[42:45], v[154:157], v[198:201], v[42:45]
	v_mfma_f32_16x16x32_bf16 v[46:49], v[140:143], v[198:201], v[46:49]
	v_mfma_f32_16x16x32_bf16 v[30:33], v[140:143], v[206:209], v[30:33]
	v_mfma_f32_16x16x32_bf16 v[26:29], v[154:157], v[206:209], v[26:29]
	v_mfma_f32_16x16x32_bf16 v[10:13], v[154:157], v[214:217], v[10:13]
	v_mfma_f32_16x16x32_bf16 v[14:17], v[140:143], v[214:217], v[14:17]
	v_mfma_f32_16x16x32_bf16 v[62:65], v[150:153], v[194:197], v[62:65]
	v_mfma_f32_16x16x32_bf16 v[58:61], v[158:161], v[194:197], v[58:61]
	v_mfma_f32_16x16x32_bf16 v[42:45], v[158:161], v[202:205], v[42:45]
	v_mfma_f32_16x16x32_bf16 v[46:49], v[150:153], v[202:205], v[46:49]
	v_mfma_f32_16x16x32_bf16 v[30:33], v[150:153], v[210:213], v[30:33]
	v_mfma_f32_16x16x32_bf16 v[26:29], v[158:161], v[210:213], v[26:29]
	v_mfma_f32_16x16x32_bf16 v[10:13], v[158:161], v[218:221], v[10:13]
	v_mfma_f32_16x16x32_bf16 v[14:17], v[150:153], v[218:221], v[14:17]
	s_setprio 0
	s_setprio 1
	v_mfma_f32_16x16x32_bf16 v[54:57], v[174:177], v[190:193], v[54:57]
	v_mfma_f32_16x16x32_bf16 v[50:53], v[182:185], v[190:193], v[50:53]
	v_mfma_f32_16x16x32_bf16 v[34:37], v[182:185], v[198:201], v[34:37]
	v_mfma_f32_16x16x32_bf16 v[38:41], v[174:177], v[198:201], v[38:41]
	v_mfma_f32_16x16x32_bf16 v[22:25], v[174:177], v[206:209], v[22:25]
	v_mfma_f32_16x16x32_bf16 v[18:21], v[182:185], v[206:209], v[18:21]
	v_mfma_f32_16x16x32_bf16 v[2:5], v[182:185], v[214:217], v[2:5]
	v_mfma_f32_16x16x32_bf16 v[6:9], v[174:177], v[214:217], v[6:9]
	v_mfma_f32_16x16x32_bf16 v[54:57], v[178:181], v[194:197], v[54:57]
	v_mfma_f32_16x16x32_bf16 v[50:53], v[186:189], v[194:197], v[50:53]
	v_mfma_f32_16x16x32_bf16 v[34:37], v[186:189], v[202:205], v[34:37]
	v_mfma_f32_16x16x32_bf16 v[38:41], v[178:181], v[202:205], v[38:41]
	v_mfma_f32_16x16x32_bf16 v[22:25], v[178:181], v[210:213], v[22:25]
	v_mfma_f32_16x16x32_bf16 v[18:21], v[186:189], v[210:213], v[18:21]
	v_mfma_f32_16x16x32_bf16 v[2:5], v[186:189], v[218:221], v[2:5]
	v_mfma_f32_16x16x32_bf16 v[6:9], v[178:181], v[218:221], v[6:9]
	s_setprio 0
	s_barrier
	s_add_i32 s83, s83, 2
	s_add_u32 s81, s81, 0x100
	s_addc_u32 s82, s82, 0
	s_cmpk_gt_u32 s83, 0x53
	s_mov_b64 s[12:13], s[16:17]
	s_cbranch_scc0 .LBB0_948
	v_lshl_add_u32 v142, s63, 8, v146
	v_lshl_or_b32 v140, s22, 8, v148
	v_lshlrev_b32_e32 v141, 12, v142
	v_lshl_add_u32 v150, v140, 1, v141
	v_add_u32_e32 v151, 0x10000, v150
	v_add_u32_e32 v152, 0x20000, v150
	v_add_u32_e32 v153, 0x30000, v150
	v_add_u32_e32 v154, 0x80000, v150
	v_add_u32_e32 v155, 0x90000, v150
	v_add_u32_e32 v156, 0xa0000, v150
	v_add_u32_e32 v157, 0xb0000, v150
	global_load_dwordx4 v[174:177], v150, s[20:21]
	global_load_dwordx4 v[178:181], v150, s[20:21] offset:64
	global_load_dwordx4 v[182:185], v151, s[20:21]
	global_load_dwordx4 v[186:189], v151, s[20:21] offset:64
	global_load_dwordx4 v[190:193], v152, s[20:21]
	global_load_dwordx4 v[194:197], v152, s[20:21] offset:64
	global_load_dwordx4 v[198:201], v153, s[20:21]
	global_load_dwordx4 v[202:205], v153, s[20:21] offset:64
	global_load_dwordx4 v[206:209], v154, s[20:21]
	global_load_dwordx4 v[210:213], v154, s[20:21] offset:64
	global_load_dwordx4 v[214:217], v155, s[20:21]
	global_load_dwordx4 v[218:221], v155, s[20:21] offset:64
	global_load_dwordx4 v[222:225], v156, s[20:21]
	global_load_dwordx4 v[226:229], v156, s[20:21] offset:64
	global_load_dwordx4 v[230:233], v157, s[20:21]
	global_load_dwordx4 v[234:237], v157, s[20:21] offset:64
	s_lshl_b32 s44, s22, 4
	s_lshl_b32 s45, s57, 2
	s_add_i32 s44, s44, s45
	v_lshl_add_u32 v158, v142, 7, s44
	v_add_u32_e32 v159, 0x1000, v158
	v_add_u32_e32 v160, 0x4000, v158
	v_add_u32_e32 v161, 0x5000, v158
	v_xor_b32_e32 v239, 16, v241
	v_xor_b32_e32 v252, 32, v241
	v_lshlrev_b32_e32 v239, 2, v239
	v_lshlrev_b32_e32 v252, 2, v252
	s_and_b64 vcc, exec, s[40:41]
	s_cbranch_vccz .LBB0_951
	s_barrier
